# attention 8-step loops (modes 0 and 2): K/V tile loads in SADDR form (scalar base in vcc + per-lane 32-bit offset), removing one 64-bit VALU add per load
# speedup vs baseline: 1.0083x; 1.0083x over previous
.LBB0_639:
	v_mov_b32_e32 v184, v222
	s_lshl_b32 s2, s0, 2
	v_readfirstlane_b32 s18, v184
	s_ashr_i32 s19, s18, 8
	s_bfe_u32 s22, s18, 0x20006
	s_lshl_b32 s12, s73, 7
	s_or_b32 s2, s2, s74
	s_lshl_b32 s1, s22, 5
	s_lshl_b32 s24, s19, 5
	s_mul_i32 s23, s2, 0x4100
	s_ashr_i32 s25, s12, 31
	s_mul_hi_u32 s13, s2, 0x4100
	s_add_u32 s23, s23, s12
	v_and_b32_e32 v181, 31, v184
	s_addc_u32 s13, s13, s25
	s_or_b32 s23, s23, s1
	v_or_b32_e32 v2, s23, v181
	v_mov_b32_e32 v3, s13
	v_lshlrev_b64 v[2:3], 7, v[2:3]
	v_lshl_add_u64 v[2:3], s[6:7], 0, v[2:3]
	s_ashr_i32 s25, s24, 31
	v_bfe_u32 v180, v184, 5, 1
	v_lshl_add_u64 v[2:3], s[24:25], 1, v[2:3]
	s_mul_i32 s24, s2, 0x208000
	s_mul_hi_u32 s23, s2, 0x208000
	v_lshlrev_b32_e32 v162, 4, v180
	v_mov_b32_e32 v163, v0
	s_add_u32 s26, s11, s24
	v_lshl_add_u64 v[2:3], v[2:3], 0, v[162:163]
	s_addc_u32 s27, s72, s23
	v_ashrrev_i32_e32 v52, 3, v184
	global_load_dwordx4 v[158:161], v[2:3], off
	global_load_dwordx4 v[154:157], v[2:3], off offset:32
	s_add_u32 s28, s36, s24
	v_ashrrev_i32_e32 v53, 31, v52
	v_mov_b64_e32 v[2:3], s[26:27]
	v_lshlrev_b32_e32 v1, 4, v184
	s_addc_u32 s29, s10, s23
	v_lshlrev_b64 v[32:33], 7, v[52:53]
	v_mad_i64_i32 v[2:3], s[26:27], v52, s55, v[2:3]
	v_and_b32_e32 v50, 0x70, v1
	v_mov_b32_e32 v51, v0
	v_lshl_add_u64 v[166:167], v[2:3], 0, v[50:51]
	v_lshl_add_u64 v[2:3], s[28:29], 0, v[32:33]
	v_lshl_add_u64 v[168:169], v[2:3], 0, v[50:51]
	s_nop 1
	v_readfirstlane_b32 s100, v168
	v_readfirstlane_b32 s101, v169
	v_readfirstlane_b32 s98, v166
	v_readfirstlane_b32 s99, v167
	s_nop 1
	v_subrev_u32_e32 v248, s100, v168
	v_subrev_u32_e32 v249, s98, v166
	v_add_co_u32_e32 v46, vcc, s3, v168
	v_mov_b32_e32 v14, v0
	v_mov_b32_e32 v15, v0
	v_addc_co_u32_e32 v47, vcc, 0, v169, vcc
	v_mov_b32_e32 v1, v0
	v_mov_b32_e32 v2, v0
	v_mov_b32_e32 v3, v0
	v_mov_b32_e32 v4, v0
	v_mov_b32_e32 v5, v0
	v_mov_b32_e32 v6, v0
	v_mov_b32_e32 v7, v0
	v_mov_b32_e32 v8, v0
	v_mov_b32_e32 v9, v0
	v_mov_b32_e32 v10, v0
	v_mov_b32_e32 v11, v0
	v_mov_b32_e32 v12, v0
	v_mov_b32_e32 v13, v0
	v_mov_b64_e32 v[30:31], v[14:15]
	v_add_co_u32_e32 v54, vcc, s59, v168
	v_mov_b64_e32 v[28:29], v[12:13]
	v_mov_b64_e32 v[26:27], v[10:11]
	v_mov_b64_e32 v[24:25], v[8:9]
	v_mov_b64_e32 v[22:23], v[6:7]
	v_mov_b64_e32 v[20:21], v[4:5]
	v_mov_b64_e32 v[18:19], v[2:3]
	v_mov_b64_e32 v[16:17], v[0:1]
	v_addc_co_u32_e32 v55, vcc, 0, v169, vcc
	global_load_dwordx4 v[34:37], v[168:169], off
	global_load_dwordx4 v[38:41], v[166:167], off
	global_load_dwordx4 v[42:45], v[166:167], off offset:128
	s_nop 0
	global_load_dwordx4 v[46:49], v[46:47], off
	s_nop 0
	global_load_dwordx4 v[54:57], v[54:55], off
	v_mad_u64_u32 v[164:165], s[26:27], v52, s60, v[50:51]
	v_add_co_u32_e32 v50, vcc, s33, v168
	s_cmp_gt_i32 s73, 1
	v_add_u32_e32 v182, 0, v164
	v_addc_co_u32_e32 v51, vcc, 0, v169, vcc
	s_cselect_b32 s92, 0x8000, s33
	global_load_dwordx4 v[58:61], v[166:167], off offset:256
	global_load_dwordx4 v[62:65], v[50:51], off
	s_cselect_b32 s2, 0x104, 4
	s_mov_b32 s25, 1
	s_add_i32 s13, s2, -1
	s_cmp_lt_i32 s73, 2
	s_barrier
	s_waitcnt vmcnt(5)
	ds_write_b128 v182, v[38:41] offset:36864
	s_waitcnt vmcnt(4)
	ds_write_b128 v182, v[42:45] offset:46080
	ds_write_b128 v182, v[34:37]
	s_waitcnt vmcnt(3)
	ds_write_b128 v182, v[46:49] offset:9216
	s_waitcnt vmcnt(2)
	ds_write_b128 v182, v[54:57] offset:18432
	v_lshl_add_u64 v[34:35], v[168:169], 0, s[92:93]
	s_waitcnt lgkmcnt(0)
	s_barrier
	global_load_dwordx4 v[138:141], v[34:35], off
	global_load_dwordx4 v[142:145], v[166:167], off offset:384
	v_mul_u32_u24_e32 v34, 0x90, v181
	v_add3_u32 v163, 0, v34, v162
	v_lshl_add_u32 v165, s19, 6, v163
	ds_read_b128 v[54:57], v165
	s_waitcnt lgkmcnt(0)
	v_mfma_f32_32x32x16_bf16 v[36:51], v[54:57], v[158:161], v[16:31]
	ds_read_b128 v[54:57], v165 offset:4608
	s_waitcnt lgkmcnt(0)
	v_mfma_f32_32x32x16_bf16 v[16:31], v[54:57], v[158:161], v[16:31]
	ds_read_b128 v[54:57], v165 offset:32
	s_waitcnt lgkmcnt(0)
	v_mfma_f32_32x32x16_bf16 v[36:51], v[54:57], v[154:157], v[36:51]
	ds_read_b128 v[54:57], v165 offset:4640
	v_max3_f32 v34, v36, v37, v38
	s_nop 0
	v_max3_f32 v34, v34, v39, v40
	s_nop 0
	v_max3_f32 v34, v34, v41, v42
	s_nop 0
	v_max3_f32 v34, v34, v43, v44
	s_waitcnt lgkmcnt(0)
	v_mfma_f32_32x32x16_bf16 v[16:31], v[54:57], v[154:157], v[16:31]
	v_max3_f32 v34, v34, v45, v46
	s_nop 0
	v_max3_f32 v34, v34, v47, v48
	s_nop 0
	v_max3_f32 v34, v34, v49, v50
	s_nop 0
	v_max3_f32 v34, v34, v51, v16
	s_nop 0
	v_max3_f32 v34, v34, v17, v18
	s_nop 0
	v_max3_f32 v34, v34, v19, v20
	s_nop 0
	v_max3_f32 v34, v34, v21, v22
	s_nop 0
	v_max3_f32 v34, v34, v23, v24
	s_nop 0
	v_max3_f32 v34, v34, v25, v26
	s_nop 0
	v_max3_f32 v34, v34, v27, v28
	s_nop 0
	v_max3_f32 v34, v34, v29, v30
	s_nop 0
	v_max3_f32 v34, v34, v31, v31
	s_setprio 0
	ds_read_b128 v[54:57], v165 offset:9216
	ds_read_b128 v[106:109], v165 offset:9248
	ds_read_b128 v[110:113], v165 offset:13824
	ds_read_b128 v[114:117], v165 offset:13856
	v_mov_b32_e32 v35, v34
	s_nop 1
	v_permlane32_swap_b32_e32 v34, v35
	v_max_f32_e32 v35, v35, v35
	v_max_f32_e32 v34, v34, v34
	v_max_f32_e32 v35, v34, v35
	v_add_f32_e32 v183, 0, v35
	v_xor_b32_e32 v34, 0x80000000, v183
	v_sub_f32_e32 v53, v36, v35
	v_sub_f32_e32 v16, v16, v35
	v_sub_f32_e32 v66, v37, v35
	v_sub_f32_e32 v17, v17, v35
	v_sub_f32_e32 v67, v38, v35
	v_sub_f32_e32 v18, v18, v35
	v_sub_f32_e32 v68, v39, v35
	v_sub_f32_e32 v19, v19, v35
	v_sub_f32_e32 v69, v40, v35
	v_sub_f32_e32 v20, v20, v35
	v_sub_f32_e32 v70, v41, v35
	v_sub_f32_e32 v21, v21, v35
	v_sub_f32_e32 v71, v42, v35
	v_sub_f32_e32 v22, v22, v35
	v_sub_f32_e32 v72, v43, v35
	v_sub_f32_e32 v23, v23, v35
	v_sub_f32_e32 v118, v44, v35
	v_sub_f32_e32 v24, v24, v35
	v_sub_f32_e32 v119, v45, v35
	v_sub_f32_e32 v25, v25, v35
	v_sub_f32_e32 v120, v46, v35
	v_sub_f32_e32 v26, v26, v35
	v_sub_f32_e32 v121, v47, v35
	v_sub_f32_e32 v27, v27, v35
	v_sub_f32_e32 v122, v48, v35
	v_sub_f32_e32 v28, v28, v35
	v_sub_f32_e32 v123, v49, v35
	v_sub_f32_e32 v29, v29, v35
	v_sub_f32_e32 v50, v50, v35
	v_sub_f32_e32 v30, v30, v35
	v_sub_f32_e32 v51, v51, v35
	v_sub_f32_e32 v31, v31, v35
	v_mov_b32_e32 v35, v34
	v_mov_b32_e32 v36, v34
	v_mov_b32_e32 v37, v34
	v_mov_b32_e32 v38, v34
	v_mov_b32_e32 v39, v34
	v_mov_b32_e32 v40, v34
	v_mov_b32_e32 v41, v34
	v_mov_b32_e32 v42, v34
	v_mov_b32_e32 v43, v34
	v_mov_b32_e32 v44, v34
	v_mov_b32_e32 v45, v34
	v_mov_b32_e32 v46, v34
	v_mov_b32_e32 v47, v34
	v_mov_b32_e32 v48, v34
	v_mov_b32_e32 v49, v34
	s_waitcnt lgkmcnt(3)
	s_nop 4
	v_mfma_f32_32x32x16_bf16 v[82:97], v[54:57], v[158:161], v[34:49]
	v_exp_f32_e32 v102, v53
	v_exp_f32_e32 v103, v66
	v_exp_f32_e32 v104, v67
	v_exp_f32_e32 v105, v68
	s_nop 0
	v_exp_f32_e32 v98, v69
	v_exp_f32_e32 v99, v70
	v_exp_f32_e32 v100, v71
	v_exp_f32_e32 v101, v72
	s_nop 0
	s_waitcnt lgkmcnt(1)
	s_nop 4
	v_mfma_f32_32x32x16_bf16 v[66:81], v[110:113], v[158:161], v[34:49]
	v_exp_f32_e32 v194, v118
	v_exp_f32_e32 v187, v119
	v_exp_f32_e32 v186, v120
	v_exp_f32_e32 v185, v121
	s_nop 0
	v_exp_f32_e32 v133, v122
	v_exp_f32_e32 v132, v123
	v_exp_f32_e32 v131, v50
	v_exp_f32_e32 v130, v51
	s_nop 0
	v_mfma_f32_32x32x16_bf16 v[82:97], v[106:109], v[154:157], v[82:97]
	v_exp_f32_e32 v129, v16
	v_exp_f32_e32 v128, v17
	v_exp_f32_e32 v127, v18
	v_exp_f32_e32 v126, v19
	s_nop 0
	v_exp_f32_e32 v125, v20
	v_exp_f32_e32 v124, v21
	v_exp_f32_e32 v123, v22
	v_exp_f32_e32 v122, v23
	s_nop 0
	s_waitcnt lgkmcnt(0)
	v_mfma_f32_32x32x16_bf16 v[66:81], v[114:117], v[154:157], v[66:81]
	v_exp_f32_e32 v109, v24
	v_exp_f32_e32 v108, v25
	v_exp_f32_e32 v107, v26
	v_exp_f32_e32 v106, v27
	s_nop 0
	v_exp_f32_e32 v113, v28
	v_exp_f32_e32 v112, v29
	v_exp_f32_e32 v111, v30
	v_exp_f32_e32 v110, v31
	s_nop 0
	s_waitcnt vmcnt(2)
	ds_write_b128 v182, v[62:65] offset:27648
	ds_write_b128 v182, v[58:61] offset:55296
	s_cbranch_scc1 .LBB0_665
	s_add_u32 s24, s4, s24
	v_and_b32_e32 v18, 7, v184
	s_addc_u32 s25, s5, s23
	v_mad_i64_i32 v[16:17], s[26:27], v52, s55, 0
	v_lshlrev_b32_e32 v170, 4, v18
	v_lshl_add_u64 v[174:175], s[24:25], 0, v[32:33]
	v_mov_b64_e32 v[32:33], v[14:15]
	v_lshl_add_u64 v[172:173], s[24:25], 0, v[16:17]
	v_mov_b64_e32 v[30:31], v[12:13]
	v_mov_b64_e32 v[28:29], v[10:11]
	v_mov_b64_e32 v[26:27], v[8:9]
	v_mov_b64_e32 v[24:25], v[6:7]
	v_mov_b64_e32 v[22:23], v[4:5]
	v_mov_b64_e32 v[20:21], v[2:3]
	v_mov_b64_e32 v[18:19], v[0:1]
	v_mov_b64_e32 v[16:17], v[14:15]
	v_mov_b32_e32 v171, v0
	s_mov_b32 s25, 1
	v_mov_b32_e32 v50, 0
	s_mov_b32 s23, 12
	v_mov_b64_e32 v[14:15], v[12:13]
	v_mov_b64_e32 v[12:13], v[10:11]
	v_mov_b64_e32 v[10:11], v[8:9]
	v_mov_b64_e32 v[8:9], v[6:7]
	v_mov_b64_e32 v[6:7], v[4:5]
	v_mov_b64_e32 v[4:5], v[2:3]
	v_mov_b64_e32 v[2:3], v[0:1]
.LBB0_641:
	v_lshl_add_u64 v[178:179], v[174:175], 0, v[170:171]
	s_mov_b32 s24, 0x1894a000
	v_add_co_u32_e32 v52, vcc, s24, v178
	v_lshl_add_u64 v[56:57], v[172:173], 0, v[170:171]
	s_nop 0
	v_addc_co_u32_e32 v53, vcc, 0, v179, vcc
	s_mov_b32 s24, 0x19980000
	v_add_co_u32_e32 v176, vcc, s24, v56
	s_nop 0
	v_addc_co_u32_e32 v177, vcc, 0, v57, vcc
	global_load_dwordx4 v[52:55], v[52:53], off
	s_mul_i32 s26, s25, 0x2400
	global_load_dwordx4 v[56:59], v[176:177], off offset:512
	s_add_i32 s24, s23, -7
	s_add_i32 s27, s26, 0xffffdc00
	s_cmp_lg_u32 s25, 0
	s_cselect_b32 s27, s27, 0x9000
	v_add_u32_e32 v1, s27, v163
	ds_read_b128 v[60:63], v1 offset:36864
	ds_read_b128 v[114:117], v1 offset:36896
	ds_read_b128 v[118:121], v1 offset:41472
	ds_read_b128 v[134:137], v1 offset:41504
	ds_read_b128 v[146:149], v1 offset:36928
	ds_read_b128 v[150:153], v1 offset:36960
	ds_read_b128 v[196:199], v1 offset:41536
	ds_read_b128 v[200:203], v1 offset:41568
	s_setprio 3
	v_cvt_pk_bf16_f32 v204, v102, v103
	v_cvt_pk_bf16_f32 v205, v104, v105
	v_cvt_pk_bf16_f32 v206, v98, v99
	v_cvt_pk_bf16_f32 v207, v100, v101
	s_waitcnt lgkmcnt(7)
	s_nop 0
	v_mfma_f32_32x32x16_bf16 v[18:33], v[60:63], v[204:207], v[18:33]
	v_mov_b32_e32 v1, v102
	v_add_f32_e32 v1, v1, v103
	v_add_f32_e32 v1, v1, v104
	v_add_f32_e32 v1, v1, v105
	s_waitcnt lgkmcnt(5)
	v_mfma_f32_32x32x16_bf16 v[2:17], v[118:121], v[204:207], v[2:17]
	v_cvt_pk_bf16_f32 v60, v194, v187
	v_cvt_pk_bf16_f32 v61, v186, v185
	v_cvt_pk_bf16_f32 v62, v133, v132
	v_cvt_pk_bf16_f32 v63, v131, v130
	v_add_f32_e32 v1, v1, v98
	v_add_f32_e32 v1, v1, v99
	v_add_f32_e32 v1, v1, v100
	v_add_f32_e32 v1, v1, v101
	s_nop 0
	v_mfma_f32_32x32x16_bf16 v[18:33], v[114:117], v[60:63], v[18:33]
	v_add_f32_e32 v1, v1, v194
	v_add_f32_e32 v1, v1, v187
	v_add_f32_e32 v1, v1, v186
	v_add_f32_e32 v1, v1, v185
	s_waitcnt lgkmcnt(4)
	v_mfma_f32_32x32x16_bf16 v[2:17], v[134:137], v[60:63], v[2:17]
	v_cvt_pk_bf16_f32 v98, v129, v128
	v_cvt_pk_bf16_f32 v99, v127, v126
	v_cvt_pk_bf16_f32 v100, v125, v124
	v_cvt_pk_bf16_f32 v101, v123, v122
	v_add_f32_e32 v1, v1, v133
	v_add_f32_e32 v1, v1, v132
	v_add_f32_e32 v1, v1, v131
	v_add_f32_e32 v1, v1, v130
	s_waitcnt lgkmcnt(3)
	v_mfma_f32_32x32x16_bf16 v[18:33], v[146:149], v[98:101], v[18:33]
	v_add_f32_e32 v1, v1, v129
	v_add_f32_e32 v1, v1, v128
	v_add_f32_e32 v1, v1, v127
	v_add_f32_e32 v1, v1, v126
	s_waitcnt lgkmcnt(1)
	v_mfma_f32_32x32x16_bf16 v[2:17], v[196:199], v[98:101], v[2:17]
	v_cvt_pk_bf16_f32 v60, v109, v108
	v_cvt_pk_bf16_f32 v61, v107, v106
	v_cvt_pk_bf16_f32 v62, v113, v112
	v_cvt_pk_bf16_f32 v63, v111, v110
	v_add_f32_e32 v1, v1, v125
	v_add_f32_e32 v1, v1, v124
	v_add_f32_e32 v1, v1, v123
	v_add_f32_e32 v1, v1, v122
	s_nop 0
	v_mfma_f32_32x32x16_bf16 v[18:33], v[150:153], v[60:63], v[18:33]
	v_add_f32_e32 v1, v1, v109
	v_add_f32_e32 v1, v1, v108
	v_add_f32_e32 v1, v1, v107
	v_add_f32_e32 v1, v1, v106
	s_waitcnt lgkmcnt(0)
	v_mfma_f32_32x32x16_bf16 v[2:17], v[200:203], v[60:63], v[2:17]
	v_add_f32_e32 v1, v1, v113
	v_add_f32_e32 v1, v1, v112
	v_add_f32_e32 v1, v1, v111
	v_add_f32_e32 v1, v1, v110
	s_setprio 2
	s_waitcnt lgkmcnt(0)
	s_barrier
	ds_read_b128 v[240:243], v165 offset:18432
	ds_read_b128 v[244:247], v165 offset:23040
	ds_read_b128 v[130:133], v165 offset:18464
	ds_read_b128 v[146:149], v165 offset:23072
	s_waitcnt lgkmcnt(2)
	v_mfma_f32_32x32x16_bf16 v[114:129], v[240:243], v[158:161], v[34:49]
	v_exp_f32_e32 v185, v82
	v_exp_f32_e32 v186, v83
	v_exp_f32_e32 v187, v84
	v_exp_f32_e32 v194, v85
	v_exp_f32_e32 v195, v86
	v_exp_f32_e32 v196, v87
	v_exp_f32_e32 v197, v88
	v_exp_f32_e32 v198, v89
	s_waitcnt lgkmcnt(1)
	v_mfma_f32_32x32x16_bf16 v[98:113], v[244:247], v[158:161], v[34:49]
	v_exp_f32_e32 v199, v90
	v_exp_f32_e32 v200, v91
	v_exp_f32_e32 v201, v92
	v_exp_f32_e32 v202, v93
	v_exp_f32_e32 v134, v94
	v_exp_f32_e32 v135, v95
	v_exp_f32_e32 v136, v96
	v_exp_f32_e32 v137, v97
	v_mfma_f32_32x32x16_bf16 v[114:129], v[130:133], v[154:157], v[114:129]
	v_exp_f32_e32 v96, v66
	v_exp_f32_e32 v97, v67
	v_exp_f32_e32 v203, v68
	v_exp_f32_e32 v204, v69
	v_exp_f32_e32 v130, v70
	v_exp_f32_e32 v131, v71
	v_exp_f32_e32 v132, v72
	v_exp_f32_e32 v133, v73
	s_waitcnt lgkmcnt(0)
	v_mfma_f32_32x32x16_bf16 v[98:113], v[146:149], v[154:157], v[98:113]
	v_exp_f32_e32 v205, v74
	v_exp_f32_e32 v206, v75
	v_exp_f32_e32 v207, v76
	v_exp_f32_e32 v208, v77
	v_exp_f32_e32 v209, v78
	v_exp_f32_e32 v210, v79
	v_exp_f32_e32 v211, v80
	v_exp_f32_e32 v212, v81
	s_cmp_gt_i32 s25, 2
	s_cselect_b32 s27, -3, 2
	s_add_i32 s27, s27, s25
	v_add_u32_e32 v88, s26, v163
	s_add_i32 s26, s23, -6
	s_mulk_i32 s27, 0x2400
	s_min_u32 s26, s26, s13
	v_add_u32_e32 v51, s27, v182
	s_min_u32 s24, s24, s13
	s_lshl_b32 s92, s26, 13
	s_waitcnt vmcnt(3)
	ds_write_b128 v182, v[138:141]
	s_waitcnt vmcnt(2)
	ds_write_b128 v51, v[142:145] offset:36864
	v_add_f32_e32 v1, v50, v1
	s_add_u32 vcc_lo, s100, s92
	s_addc_u32 vcc_hi, s101, 0
	global_load_dwordx4 v[146:149], v248, vcc
	s_lshl_b32 s92, s24, 7
	s_add_u32 vcc_lo, s98, s92
	s_addc_u32 vcc_hi, s99, 0
	global_load_dwordx4 v[150:153], v249, vcc
	ds_read_b128 v[240:243], v165 offset:27648
	ds_read_b128 v[244:247], v165 offset:32256
	ds_read_b128 v[60:63], v88 offset:41472
	ds_read_b128 v[64:67], v88 offset:36864
	ds_read_b128 v[68:71], v88 offset:36896
	ds_read_b128 v[72:75], v88 offset:41504
	ds_read_b128 v[76:79], v88 offset:36928
	ds_read_b128 v[80:83], v88 offset:41536
	ds_read_b128 v[84:87], v88 offset:36960
	ds_read_b128 v[88:91], v88 offset:41568
	s_add_i32 s27, s25, 1
	s_setprio 1
	v_cvt_pk_bf16_f32 v92, v185, v186
	v_cvt_pk_bf16_f32 v93, v187, v194
	v_cvt_pk_bf16_f32 v94, v195, v196
	v_cvt_pk_bf16_f32 v95, v197, v198
	s_waitcnt lgkmcnt(6)
	s_nop 0
	v_mfma_f32_32x32x16_bf16 v[18:33], v[64:67], v[92:95], v[18:33]
	v_mov_b32_e32 v213, v185
	v_add_f32_e32 v213, v213, v186
	v_add_f32_e32 v213, v213, v187
	v_add_f32_e32 v213, v213, v194
	s_nop 0
	v_mfma_f32_32x32x16_bf16 v[2:17], v[60:63], v[92:95], v[2:17]
	v_cvt_pk_bf16_f32 v64, v199, v200
	v_cvt_pk_bf16_f32 v65, v201, v202
	v_cvt_pk_bf16_f32 v66, v134, v135
	v_cvt_pk_bf16_f32 v67, v136, v137
	v_add_f32_e32 v213, v213, v195
	v_add_f32_e32 v213, v213, v196
	v_add_f32_e32 v213, v213, v197
	v_add_f32_e32 v213, v213, v198
	s_waitcnt lgkmcnt(5)
	v_mfma_f32_32x32x16_bf16 v[18:33], v[68:71], v[64:67], v[18:33]
	v_add_f32_e32 v213, v213, v199
	v_add_f32_e32 v213, v213, v200
	v_add_f32_e32 v213, v213, v201
	v_add_f32_e32 v213, v213, v202
	s_waitcnt lgkmcnt(4)
	v_mfma_f32_32x32x16_bf16 v[2:17], v[72:75], v[64:67], v[2:17]
	v_cvt_pk_bf16_f32 v60, v96, v97
	v_cvt_pk_bf16_f32 v61, v203, v204
	v_cvt_pk_bf16_f32 v62, v130, v131
	v_cvt_pk_bf16_f32 v63, v132, v133
	v_add_f32_e32 v213, v213, v134
	v_add_f32_e32 v213, v213, v135
	v_add_f32_e32 v213, v213, v136
	v_add_f32_e32 v213, v213, v137
	s_waitcnt lgkmcnt(3)
	v_mfma_f32_32x32x16_bf16 v[18:33], v[76:79], v[60:63], v[18:33]
	v_add_f32_e32 v213, v213, v96
	v_add_f32_e32 v213, v213, v97
	v_add_f32_e32 v213, v213, v203
	v_add_f32_e32 v213, v213, v204
	s_waitcnt lgkmcnt(2)
	v_mfma_f32_32x32x16_bf16 v[2:17], v[80:83], v[60:63], v[2:17]
	v_cvt_pk_bf16_f32 v64, v205, v206
	v_cvt_pk_bf16_f32 v65, v207, v208
	v_cvt_pk_bf16_f32 v66, v209, v210
	v_cvt_pk_bf16_f32 v67, v211, v212
	v_add_f32_e32 v213, v213, v130
	v_add_f32_e32 v213, v213, v131
	v_add_f32_e32 v213, v213, v132
	v_add_f32_e32 v213, v213, v133
	s_waitcnt lgkmcnt(1)
	v_mfma_f32_32x32x16_bf16 v[18:33], v[84:87], v[64:67], v[18:33]
	v_add_f32_e32 v213, v213, v205
	v_add_f32_e32 v213, v213, v206
	v_add_f32_e32 v213, v213, v207
	v_add_f32_e32 v213, v213, v208
	s_waitcnt lgkmcnt(0)
	v_mfma_f32_32x32x16_bf16 v[2:17], v[88:91], v[64:67], v[2:17]
	v_add_f32_e32 v213, v213, v209
	v_add_f32_e32 v213, v213, v210
	v_add_f32_e32 v213, v213, v211
	v_add_f32_e32 v213, v213, v212
	s_setprio 0
	ds_read_b128 v[64:67], v165 offset:27680
	ds_read_b128 v[72:75], v165 offset:32288
	s_cmp_lg_u32 s25, 4
	s_cselect_b32 s24, s27, 0
	s_waitcnt lgkmcnt(2)
	v_mfma_f32_32x32x16_bf16 v[130:145], v[240:243], v[158:161], v[34:49]
	v_exp_f32_e32 v185, v114
	v_exp_f32_e32 v186, v115
	v_exp_f32_e32 v187, v116
	v_exp_f32_e32 v194, v117
	v_exp_f32_e32 v195, v118
	v_exp_f32_e32 v196, v119
	v_exp_f32_e32 v197, v120
	v_exp_f32_e32 v198, v121
	s_waitcnt lgkmcnt(1)
	v_mfma_f32_32x32x16_bf16 v[82:97], v[244:247], v[158:161], v[34:49]
	v_exp_f32_e32 v199, v122
	v_exp_f32_e32 v200, v123
	v_exp_f32_e32 v201, v124
	v_exp_f32_e32 v202, v125
	v_exp_f32_e32 v122, v126
	v_exp_f32_e32 v123, v127
	v_exp_f32_e32 v124, v128
	v_exp_f32_e32 v125, v129
	v_mfma_f32_32x32x16_bf16 v[130:145], v[64:67], v[154:157], v[130:145]
	v_exp_f32_e32 v126, v98
	v_exp_f32_e32 v127, v99
	v_exp_f32_e32 v128, v100
	v_exp_f32_e32 v129, v101
	v_exp_f32_e32 v203, v102
	v_exp_f32_e32 v204, v103
	v_exp_f32_e32 v205, v104
	v_exp_f32_e32 v206, v105
	s_waitcnt lgkmcnt(0)
	v_mfma_f32_32x32x16_bf16 v[82:97], v[72:75], v[154:157], v[82:97]
	v_exp_f32_e32 v102, v106
	v_exp_f32_e32 v103, v107
	v_exp_f32_e32 v104, v108
	v_exp_f32_e32 v105, v109
	v_exp_f32_e32 v106, v110
	v_exp_f32_e32 v107, v111
	v_exp_f32_e32 v108, v112
	v_exp_f32_e32 v109, v113
	s_cmp_gt_i32 s24, 2
	s_cselect_b32 s25, -3, 2
	s_add_i32 s25, s25, s24
	s_mulk_i32 s25, 0x2400
	v_add_u32_e32 v50, s25, v182
	s_add_i32 s25, s24, 1
	s_cmp_lg_u32 s24, 4
	s_cselect_b32 s24, s25, 0
	s_add_i32 s25, s23, -5
	s_min_u32 s25, s25, s13
	s_lshl_b32 s92, s25, 13
	s_waitcnt vmcnt(3)
	ds_write_b128 v182, v[52:55] offset:9216
	s_waitcnt vmcnt(2)
	ds_write_b128 v50, v[56:59] offset:36864
	s_add_u32 vcc_lo, s100, s92
	s_addc_u32 vcc_hi, s101, 0
	global_load_dwordx4 v[118:121], v248, vcc
	s_lshl_b32 s92, s26, 7
	s_add_u32 vcc_lo, s98, s92
	s_addc_u32 vcc_hi, s99, 0
	global_load_dwordx4 v[114:117], v249, vcc
	s_mul_i32 s26, s24, 0x2400
	s_add_i32 s27, s26, 0xffffdc00
	s_cmp_lg_u32 s24, 0
	s_cselect_b32 s27, s27, 0x9000
	v_add_u32_e32 v78, s27, v163
	ds_read_b128 v[50:53], v78 offset:36864
	ds_read_b128 v[54:57], v78 offset:36896
	ds_read_b128 v[58:61], v78 offset:41472
	ds_read_b128 v[62:65], v78 offset:41504
	ds_read_b128 v[66:69], v78 offset:36928
	ds_read_b128 v[70:73], v78 offset:36960
	ds_read_b128 v[74:77], v78 offset:41536
	ds_read_b128 v[78:81], v78 offset:41568
	s_setprio 3
	v_cvt_pk_bf16_f32 v98, v185, v186
	v_cvt_pk_bf16_f32 v99, v187, v194
	v_cvt_pk_bf16_f32 v100, v195, v196
	v_cvt_pk_bf16_f32 v101, v197, v198
	s_waitcnt lgkmcnt(7)
	s_nop 0
	v_mfma_f32_32x32x16_bf16 v[18:33], v[50:53], v[98:101], v[18:33]
	v_mov_b32_e32 v110, v185
	v_add_f32_e32 v110, v110, v186
	v_add_f32_e32 v110, v110, v187
	v_add_f32_e32 v110, v110, v194
	s_waitcnt lgkmcnt(5)
	v_mfma_f32_32x32x16_bf16 v[2:17], v[58:61], v[98:101], v[2:17]
	v_cvt_pk_bf16_f32 v50, v199, v200
	v_cvt_pk_bf16_f32 v51, v201, v202
	v_cvt_pk_bf16_f32 v52, v122, v123
	v_cvt_pk_bf16_f32 v53, v124, v125
	v_add_f32_e32 v110, v110, v195
	v_add_f32_e32 v110, v110, v196
	v_add_f32_e32 v110, v110, v197
	v_add_f32_e32 v110, v110, v198
	s_nop 0
	v_mfma_f32_32x32x16_bf16 v[18:33], v[54:57], v[50:53], v[18:33]
	v_add_f32_e32 v110, v110, v199
	v_add_f32_e32 v110, v110, v200
	v_add_f32_e32 v110, v110, v201
	v_add_f32_e32 v110, v110, v202
	s_waitcnt lgkmcnt(4)
	v_mfma_f32_32x32x16_bf16 v[2:17], v[62:65], v[50:53], v[2:17]
	v_cvt_pk_bf16_f32 v54, v126, v127
	v_cvt_pk_bf16_f32 v55, v128, v129
	v_cvt_pk_bf16_f32 v56, v203, v204
	v_cvt_pk_bf16_f32 v57, v205, v206
	v_add_f32_e32 v110, v110, v122
	v_add_f32_e32 v110, v110, v123
	v_add_f32_e32 v110, v110, v124
	v_add_f32_e32 v110, v110, v125
	s_waitcnt lgkmcnt(3)
	v_mfma_f32_32x32x16_bf16 v[18:33], v[66:69], v[54:57], v[18:33]
	v_add_f32_e32 v110, v110, v126
	v_add_f32_e32 v110, v110, v127
	v_add_f32_e32 v110, v110, v128
	v_add_f32_e32 v110, v110, v129
	s_waitcnt lgkmcnt(1)
	v_mfma_f32_32x32x16_bf16 v[2:17], v[74:77], v[54:57], v[2:17]
	v_cvt_pk_bf16_f32 v50, v102, v103
	v_cvt_pk_bf16_f32 v51, v104, v105
	v_cvt_pk_bf16_f32 v52, v106, v107
	v_cvt_pk_bf16_f32 v53, v108, v109
	v_add_f32_e32 v110, v110, v203
	v_add_f32_e32 v110, v110, v204
	v_add_f32_e32 v110, v110, v205
	v_add_f32_e32 v110, v110, v206
	s_nop 0
	v_mfma_f32_32x32x16_bf16 v[18:33], v[70:73], v[50:53], v[18:33]
	v_add_f32_e32 v110, v110, v102
	v_add_f32_e32 v110, v110, v103
	v_add_f32_e32 v110, v110, v104
	v_add_f32_e32 v110, v110, v105
	s_waitcnt lgkmcnt(0)
	v_mfma_f32_32x32x16_bf16 v[2:17], v[78:81], v[50:53], v[2:17]
	v_add_f32_e32 v110, v110, v106
	v_add_f32_e32 v110, v110, v107
	v_add_f32_e32 v110, v110, v108
	v_add_f32_e32 v110, v110, v109
	s_setprio 2
	s_waitcnt lgkmcnt(0)
	s_barrier
	ds_read_b128 v[240:243], v165
	ds_read_b128 v[244:247], v165 offset:4608
	ds_read_b128 v[102:105], v165 offset:32
	ds_read_b128 v[106:109], v165 offset:4640
	v_add_f32_e32 v1, v1, v213
	s_waitcnt lgkmcnt(2)
	v_mfma_f32_32x32x16_bf16 v[66:81], v[240:243], v[158:161], v[34:49]
	v_exp_f32_e32 v185, v130
	v_exp_f32_e32 v186, v131
	v_exp_f32_e32 v187, v132
	v_exp_f32_e32 v194, v133
	v_exp_f32_e32 v195, v134
	v_exp_f32_e32 v196, v135
	v_exp_f32_e32 v197, v136
	v_exp_f32_e32 v198, v137
	v_mfma_f32_32x32x16_bf16 v[50:65], v[244:247], v[158:161], v[34:49]
	v_exp_f32_e32 v134, v138
	v_exp_f32_e32 v135, v139
	v_exp_f32_e32 v136, v140
	v_exp_f32_e32 v137, v141
	v_exp_f32_e32 v138, v142
	v_exp_f32_e32 v139, v143
	v_exp_f32_e32 v140, v144
	v_exp_f32_e32 v141, v145
	s_waitcnt lgkmcnt(1)
	v_mfma_f32_32x32x16_bf16 v[66:81], v[102:105], v[154:157], v[66:81]
	v_exp_f32_e32 v142, v82
	v_exp_f32_e32 v143, v83
	v_exp_f32_e32 v144, v84
	v_exp_f32_e32 v145, v85
	v_exp_f32_e32 v199, v86
	v_exp_f32_e32 v200, v87
	v_exp_f32_e32 v201, v88
	v_exp_f32_e32 v202, v89
	s_waitcnt lgkmcnt(0)
	v_mfma_f32_32x32x16_bf16 v[50:65], v[106:109], v[154:157], v[50:65]
	v_exp_f32_e32 v203, v90
	v_exp_f32_e32 v204, v91
	v_exp_f32_e32 v205, v92
	v_exp_f32_e32 v206, v93
	v_exp_f32_e32 v207, v94
	v_exp_f32_e32 v208, v95
	v_exp_f32_e32 v209, v96
	v_exp_f32_e32 v210, v97
	s_cmp_gt_i32 s24, 2
	s_cselect_b32 s27, -3, 2
	s_add_i32 s27, s27, s24
	s_mulk_i32 s27, 0x2400
	v_add_u32_e32 v82, s27, v182
	s_mov_b32 s27, 0x18950000
	s_waitcnt vmcnt(3)
	ds_write_b128 v182, v[146:149] offset:18432
	s_waitcnt vmcnt(2)
	ds_write_b128 v82, v[150:153] offset:36864
	v_add_co_u32_e32 v82, vcc, s27, v178
	s_lshl_b32 s92, s25, 7
	s_nop 0
	v_addc_co_u32_e32 v83, vcc, 0, v179, vcc
	global_load_dwordx4 v[126:129], v[82:83], off
	s_add_u32 vcc_lo, s98, s92
	s_addc_u32 vcc_hi, s99, 0
	global_load_dwordx4 v[122:125], v249, vcc
	v_add_u32_e32 v111, s26, v163
	v_add_f32_e32 v1, v1, v110
	ds_read_b128 v[240:243], v165 offset:9216
	ds_read_b128 v[244:247], v165 offset:13824
	ds_read_b128 v[82:85], v111 offset:41472
	ds_read_b128 v[86:89], v111 offset:36864
	ds_read_b128 v[90:93], v111 offset:36896
	ds_read_b128 v[94:97], v111 offset:41504
	ds_read_b128 v[98:101], v111 offset:36928
	ds_read_b128 v[102:105], v111 offset:41536
	ds_read_b128 v[106:109], v111 offset:36960
	ds_read_b128 v[110:113], v111 offset:41568
	s_add_i32 s26, s24, 1
	s_setprio 1
	v_cvt_pk_bf16_f32 v130, v185, v186
	v_cvt_pk_bf16_f32 v131, v187, v194
	v_cvt_pk_bf16_f32 v132, v195, v196
	v_cvt_pk_bf16_f32 v133, v197, v198
	s_waitcnt lgkmcnt(6)
	s_nop 0
	v_mfma_f32_32x32x16_bf16 v[18:33], v[86:89], v[130:133], v[18:33]
	v_mov_b32_e32 v146, v185
	v_add_f32_e32 v146, v146, v186
	v_add_f32_e32 v146, v146, v187
	v_add_f32_e32 v146, v146, v194
	s_nop 0
	v_mfma_f32_32x32x16_bf16 v[2:17], v[82:85], v[130:133], v[2:17]
	v_cvt_pk_bf16_f32 v86, v134, v135
	v_cvt_pk_bf16_f32 v87, v136, v137
	v_cvt_pk_bf16_f32 v88, v138, v139
	v_cvt_pk_bf16_f32 v89, v140, v141
	v_add_f32_e32 v146, v146, v195
	v_add_f32_e32 v146, v146, v196
	v_add_f32_e32 v146, v146, v197
	v_add_f32_e32 v146, v146, v198
	s_waitcnt lgkmcnt(5)
	v_mfma_f32_32x32x16_bf16 v[18:33], v[90:93], v[86:89], v[18:33]
	v_add_f32_e32 v146, v146, v134
	v_add_f32_e32 v146, v146, v135
	v_add_f32_e32 v146, v146, v136
	v_add_f32_e32 v146, v146, v137
	s_waitcnt lgkmcnt(4)
	v_mfma_f32_32x32x16_bf16 v[2:17], v[94:97], v[86:89], v[2:17]
	v_cvt_pk_bf16_f32 v82, v142, v143
	v_cvt_pk_bf16_f32 v83, v144, v145
	v_cvt_pk_bf16_f32 v84, v199, v200
	v_cvt_pk_bf16_f32 v85, v201, v202
	v_add_f32_e32 v146, v146, v138
	v_add_f32_e32 v146, v146, v139
	v_add_f32_e32 v146, v146, v140
	v_add_f32_e32 v146, v146, v141
	s_waitcnt lgkmcnt(3)
	v_mfma_f32_32x32x16_bf16 v[18:33], v[98:101], v[82:85], v[18:33]
	v_add_f32_e32 v146, v146, v142
	v_add_f32_e32 v146, v146, v143
	v_add_f32_e32 v146, v146, v144
	v_add_f32_e32 v146, v146, v145
	s_waitcnt lgkmcnt(2)
	v_mfma_f32_32x32x16_bf16 v[2:17], v[102:105], v[82:85], v[2:17]
	v_cvt_pk_bf16_f32 v86, v203, v204
	v_cvt_pk_bf16_f32 v87, v205, v206
	v_cvt_pk_bf16_f32 v88, v207, v208
	v_cvt_pk_bf16_f32 v89, v209, v210
	v_add_f32_e32 v146, v146, v199
	v_add_f32_e32 v146, v146, v200
	v_add_f32_e32 v146, v146, v201
	v_add_f32_e32 v146, v146, v202
	s_waitcnt lgkmcnt(1)
	v_mfma_f32_32x32x16_bf16 v[18:33], v[106:109], v[86:89], v[18:33]
	v_add_f32_e32 v146, v146, v203
	v_add_f32_e32 v146, v146, v204
	v_add_f32_e32 v146, v146, v205
	v_add_f32_e32 v146, v146, v206
	s_waitcnt lgkmcnt(0)
	v_mfma_f32_32x32x16_bf16 v[2:17], v[110:113], v[86:89], v[2:17]
	v_add_f32_e32 v146, v146, v207
	v_add_f32_e32 v146, v146, v208
	v_add_f32_e32 v146, v146, v209
	v_add_f32_e32 v146, v146, v210
	s_setprio 0
	ds_read_b128 v[130:133], v165 offset:9248
	ds_read_b128 v[138:141], v165 offset:13856
	s_cmp_lg_u32 s24, 4
	s_cselect_b32 s24, s26, 0
	s_waitcnt lgkmcnt(2)
	v_mfma_f32_32x32x16_bf16 v[98:113], v[240:243], v[158:161], v[34:49]
	v_exp_f32_e32 v142, v66
	v_exp_f32_e32 v143, v67
	v_exp_f32_e32 v144, v68
	v_exp_f32_e32 v145, v69
	v_exp_f32_e32 v147, v70
	v_exp_f32_e32 v148, v71
	v_exp_f32_e32 v149, v72
	v_exp_f32_e32 v150, v73
	s_waitcnt lgkmcnt(1)
	v_mfma_f32_32x32x16_bf16 v[82:97], v[244:247], v[158:161], v[34:49]
	v_exp_f32_e32 v151, v74
	v_exp_f32_e32 v152, v75
	v_exp_f32_e32 v153, v76
	v_exp_f32_e32 v178, v77
	v_exp_f32_e32 v134, v78
	v_exp_f32_e32 v135, v79
	v_exp_f32_e32 v136, v80
	v_exp_f32_e32 v137, v81
	v_mfma_f32_32x32x16_bf16 v[98:113], v[130:133], v[154:157], v[98:113]
	v_exp_f32_e32 v179, v50
	v_exp_f32_e32 v185, v51
	v_exp_f32_e32 v186, v52
	v_exp_f32_e32 v187, v53
	v_exp_f32_e32 v194, v54
	v_exp_f32_e32 v195, v55
	v_exp_f32_e32 v196, v56
	v_exp_f32_e32 v197, v57
	s_waitcnt lgkmcnt(0)
	v_mfma_f32_32x32x16_bf16 v[82:97], v[138:141], v[154:157], v[82:97]
	v_exp_f32_e32 v198, v58
	v_exp_f32_e32 v199, v59
	v_exp_f32_e32 v200, v60
	v_exp_f32_e32 v201, v61
	v_exp_f32_e32 v138, v62
	v_exp_f32_e32 v139, v63
	v_exp_f32_e32 v140, v64
	v_exp_f32_e32 v141, v65
	s_cmp_gt_i32 s24, 2
	s_cselect_b32 s25, -3, 2
	s_add_i32 s25, s25, s24
	s_mulk_i32 s25, 0x2400
	v_add_u32_e32 v50, s25, v182
	s_add_i32 s25, s24, 1
	s_cmp_lg_u32 s24, 4
	s_cselect_b32 s25, s25, 0
	s_add_i32 s24, s23, -3
	s_min_u32 s26, s24, s13
	s_lshl_b32 s92, s26, 13
	s_waitcnt vmcnt(3)
	ds_write_b128 v182, v[118:121] offset:27648
	s_waitcnt vmcnt(2)
	ds_write_b128 v50, v[114:117] offset:36864
	s_add_u32 vcc_lo, s100, s92
	s_addc_u32 vcc_hi, s101, 0
	global_load_dwordx4 v[118:121], v248, vcc
	global_load_dwordx4 v[114:117], v[176:177], off offset:1024
	s_mul_i32 s27, s25, 0x2400
	s_add_i32 s28, s27, 0xffffdc00
	s_cmp_lg_u32 s25, 0
	s_cselect_b32 s28, s28, 0x9000
	v_add_u32_e32 v78, s28, v163
	ds_read_b128 v[50:53], v78 offset:36864
	ds_read_b128 v[54:57], v78 offset:36896
	ds_read_b128 v[58:61], v78 offset:41472
	ds_read_b128 v[62:65], v78 offset:41504
	ds_read_b128 v[66:69], v78 offset:36928
	ds_read_b128 v[70:73], v78 offset:36960
	ds_read_b128 v[74:77], v78 offset:41536
	ds_read_b128 v[78:81], v78 offset:41568
	s_setprio 3
	v_cvt_pk_bf16_f32 v130, v142, v143
	v_cvt_pk_bf16_f32 v131, v144, v145
	v_cvt_pk_bf16_f32 v132, v147, v148
	v_cvt_pk_bf16_f32 v133, v149, v150
	s_waitcnt lgkmcnt(7)
	s_nop 0
	v_mfma_f32_32x32x16_bf16 v[18:33], v[50:53], v[130:133], v[18:33]
	v_mov_b32_e32 v176, v142
	v_add_f32_e32 v176, v176, v143
	v_add_f32_e32 v176, v176, v144
	v_add_f32_e32 v176, v176, v145
	s_waitcnt lgkmcnt(5)
	v_mfma_f32_32x32x16_bf16 v[2:17], v[58:61], v[130:133], v[2:17]
	v_cvt_pk_bf16_f32 v50, v151, v152
	v_cvt_pk_bf16_f32 v51, v153, v178
	v_cvt_pk_bf16_f32 v52, v134, v135
	v_cvt_pk_bf16_f32 v53, v136, v137
	v_add_f32_e32 v176, v176, v147
	v_add_f32_e32 v176, v176, v148
	v_add_f32_e32 v176, v176, v149
	v_add_f32_e32 v176, v176, v150
	s_nop 0
	v_mfma_f32_32x32x16_bf16 v[18:33], v[54:57], v[50:53], v[18:33]
	v_add_f32_e32 v176, v176, v151
	v_add_f32_e32 v176, v176, v152
	v_add_f32_e32 v176, v176, v153
	v_add_f32_e32 v176, v176, v178
	s_waitcnt lgkmcnt(4)
	v_mfma_f32_32x32x16_bf16 v[2:17], v[62:65], v[50:53], v[2:17]
	v_cvt_pk_bf16_f32 v54, v179, v185
	v_cvt_pk_bf16_f32 v55, v186, v187
	v_cvt_pk_bf16_f32 v56, v194, v195
	v_cvt_pk_bf16_f32 v57, v196, v197
	v_add_f32_e32 v176, v176, v134
	v_add_f32_e32 v176, v176, v135
	v_add_f32_e32 v176, v176, v136
	v_add_f32_e32 v176, v176, v137
	s_waitcnt lgkmcnt(3)
	v_mfma_f32_32x32x16_bf16 v[18:33], v[66:69], v[54:57], v[18:33]
	v_add_f32_e32 v176, v176, v179
	v_add_f32_e32 v176, v176, v185
	v_add_f32_e32 v176, v176, v186
	v_add_f32_e32 v176, v176, v187
	s_waitcnt lgkmcnt(1)
	v_mfma_f32_32x32x16_bf16 v[2:17], v[74:77], v[54:57], v[2:17]
	v_cvt_pk_bf16_f32 v50, v198, v199
	v_cvt_pk_bf16_f32 v51, v200, v201
	v_cvt_pk_bf16_f32 v52, v138, v139
	v_cvt_pk_bf16_f32 v53, v140, v141
	v_add_f32_e32 v176, v176, v194
	v_add_f32_e32 v176, v176, v195
	v_add_f32_e32 v176, v176, v196
	v_add_f32_e32 v176, v176, v197
	s_nop 0
	v_mfma_f32_32x32x16_bf16 v[18:33], v[70:73], v[50:53], v[18:33]
	v_add_f32_e32 v176, v176, v198
	v_add_f32_e32 v176, v176, v199
	v_add_f32_e32 v176, v176, v200
	v_add_f32_e32 v176, v176, v201
	s_waitcnt lgkmcnt(0)
	v_mfma_f32_32x32x16_bf16 v[2:17], v[78:81], v[50:53], v[2:17]
	v_add_f32_e32 v176, v176, v138
	v_add_f32_e32 v176, v176, v139
	v_add_f32_e32 v176, v176, v140
	v_add_f32_e32 v176, v176, v141
	s_setprio 2
	s_waitcnt lgkmcnt(0)
	s_barrier
	ds_read_b128 v[240:243], v165 offset:18432
	ds_read_b128 v[244:247], v165 offset:23040
	ds_read_b128 v[134:137], v165 offset:18464
	ds_read_b128 v[138:141], v165 offset:23072
	v_add_f32_e32 v1, v1, v146
	s_waitcnt lgkmcnt(2)
	v_mfma_f32_32x32x16_bf16 v[66:81], v[240:243], v[158:161], v[34:49]
	v_exp_f32_e32 v142, v98
	v_exp_f32_e32 v143, v99
	v_exp_f32_e32 v144, v100
	v_exp_f32_e32 v145, v101
	v_exp_f32_e32 v146, v102
	v_exp_f32_e32 v147, v103
	v_exp_f32_e32 v148, v104
	v_exp_f32_e32 v149, v105
	v_mfma_f32_32x32x16_bf16 v[50:65], v[244:247], v[158:161], v[34:49]
	v_exp_f32_e32 v150, v106
	v_exp_f32_e32 v151, v107
	v_exp_f32_e32 v152, v108
	v_exp_f32_e32 v153, v109
	v_exp_f32_e32 v177, v110
	v_exp_f32_e32 v178, v111
	v_exp_f32_e32 v179, v112
	v_exp_f32_e32 v185, v113
	s_waitcnt lgkmcnt(1)
	v_mfma_f32_32x32x16_bf16 v[66:81], v[134:137], v[154:157], v[66:81]
	v_exp_f32_e32 v186, v82
	v_exp_f32_e32 v187, v83
	v_exp_f32_e32 v194, v84
	v_exp_f32_e32 v195, v85
	v_exp_f32_e32 v134, v86
	v_exp_f32_e32 v135, v87
	v_exp_f32_e32 v136, v88
	v_exp_f32_e32 v137, v89
	s_waitcnt lgkmcnt(0)
	v_mfma_f32_32x32x16_bf16 v[50:65], v[138:141], v[154:157], v[50:65]
	v_exp_f32_e32 v196, v90
	v_exp_f32_e32 v197, v91
	v_exp_f32_e32 v198, v92
	v_exp_f32_e32 v199, v93
	v_exp_f32_e32 v138, v94
	v_exp_f32_e32 v139, v95
	v_exp_f32_e32 v140, v96
	v_exp_f32_e32 v141, v97
	s_cmp_gt_i32 s25, 2
	s_cselect_b32 s28, -3, 2
	s_waitcnt vmcnt(3)
	ds_write_b128 v182, v[126:129]
	s_add_i32 s28, s28, s25
	v_add_u32_e32 v126, s27, v163
	s_add_i32 s27, s23, -2
	s_mulk_i32 s28, 0x2400
	s_min_u32 s27, s27, s13
	v_add_u32_e32 v82, s28, v182
	s_lshl_b32 s92, s27, 13
	s_waitcnt vmcnt(2)
	ds_write_b128 v82, v[122:125] offset:36864
	s_add_u32 vcc_lo, s100, s92
	s_addc_u32 vcc_hi, s101, 0
	global_load_dwordx4 v[98:101], v248, vcc
	s_lshl_b32 s92, s26, 7
	s_add_u32 vcc_lo, s98, s92
	s_addc_u32 vcc_hi, s99, 0
	global_load_dwordx4 v[102:105], v249, vcc
	ds_read_b128 v[240:243], v165 offset:27648
	ds_read_b128 v[244:247], v165 offset:32256
	ds_read_b128 v[82:85], v126 offset:41472
	ds_read_b128 v[86:89], v126 offset:36864
	ds_read_b128 v[90:93], v126 offset:36896
	ds_read_b128 v[94:97], v126 offset:41504
	ds_read_b128 v[106:109], v126 offset:36928
	ds_read_b128 v[110:113], v126 offset:41536
	ds_read_b128 v[122:125], v126 offset:36960
	ds_read_b128 v[126:129], v126 offset:41568
	v_add_f32_e32 v1, v1, v176
	s_add_i32 s28, s25, 1
	s_setprio 1
	v_cvt_pk_bf16_f32 v130, v142, v143
	v_cvt_pk_bf16_f32 v131, v144, v145
	v_cvt_pk_bf16_f32 v132, v146, v147
	v_cvt_pk_bf16_f32 v133, v148, v149
	s_waitcnt lgkmcnt(6)
	s_nop 0
	v_mfma_f32_32x32x16_bf16 v[18:33], v[86:89], v[130:133], v[18:33]
	v_mov_b32_e32 v176, v142
	v_add_f32_e32 v176, v176, v143
	v_add_f32_e32 v176, v176, v144
	v_add_f32_e32 v176, v176, v145
	s_nop 0
	v_mfma_f32_32x32x16_bf16 v[2:17], v[82:85], v[130:133], v[2:17]
	v_cvt_pk_bf16_f32 v86, v150, v151
	v_cvt_pk_bf16_f32 v87, v152, v153
	v_cvt_pk_bf16_f32 v88, v177, v178
	v_cvt_pk_bf16_f32 v89, v179, v185
	v_add_f32_e32 v176, v176, v146
	v_add_f32_e32 v176, v176, v147
	v_add_f32_e32 v176, v176, v148
	v_add_f32_e32 v176, v176, v149
	s_waitcnt lgkmcnt(5)
	v_mfma_f32_32x32x16_bf16 v[18:33], v[90:93], v[86:89], v[18:33]
	v_add_f32_e32 v176, v176, v150
	v_add_f32_e32 v176, v176, v151
	v_add_f32_e32 v176, v176, v152
	v_add_f32_e32 v176, v176, v153
	s_waitcnt lgkmcnt(4)
	v_mfma_f32_32x32x16_bf16 v[2:17], v[94:97], v[86:89], v[2:17]
	v_cvt_pk_bf16_f32 v82, v186, v187
	v_cvt_pk_bf16_f32 v83, v194, v195
	v_cvt_pk_bf16_f32 v84, v134, v135
	v_cvt_pk_bf16_f32 v85, v136, v137
	v_add_f32_e32 v176, v176, v177
	v_add_f32_e32 v176, v176, v178
	v_add_f32_e32 v176, v176, v179
	v_add_f32_e32 v176, v176, v185
	s_waitcnt lgkmcnt(3)
	v_mfma_f32_32x32x16_bf16 v[18:33], v[106:109], v[82:85], v[18:33]
	v_add_f32_e32 v176, v176, v186
	v_add_f32_e32 v176, v176, v187
	v_add_f32_e32 v176, v176, v194
	v_add_f32_e32 v176, v176, v195
	s_waitcnt lgkmcnt(2)
	v_mfma_f32_32x32x16_bf16 v[2:17], v[110:113], v[82:85], v[2:17]
	v_cvt_pk_bf16_f32 v86, v196, v197
	v_cvt_pk_bf16_f32 v87, v198, v199
	v_cvt_pk_bf16_f32 v88, v138, v139
	v_cvt_pk_bf16_f32 v89, v140, v141
	v_add_f32_e32 v176, v176, v134
	v_add_f32_e32 v176, v176, v135
	v_add_f32_e32 v176, v176, v136
	v_add_f32_e32 v176, v176, v137
	s_waitcnt lgkmcnt(1)
	v_mfma_f32_32x32x16_bf16 v[18:33], v[122:125], v[86:89], v[18:33]
	v_add_f32_e32 v176, v176, v196
	v_add_f32_e32 v176, v176, v197
	v_add_f32_e32 v176, v176, v198
	v_add_f32_e32 v176, v176, v199
	s_waitcnt lgkmcnt(0)
	v_mfma_f32_32x32x16_bf16 v[2:17], v[126:129], v[86:89], v[2:17]
	v_add_f32_e32 v176, v176, v138
	v_add_f32_e32 v176, v176, v139
	v_add_f32_e32 v176, v176, v140
	v_add_f32_e32 v176, v176, v141
	s_setprio 0
	ds_read_b128 v[106:109], v165 offset:27680
	ds_read_b128 v[122:125], v165 offset:32288
	s_cmp_lg_u32 s25, 4
	s_cselect_b32 s25, s28, 0
	s_waitcnt lgkmcnt(2)
	v_mfma_f32_32x32x16_bf16 v[138:153], v[240:243], v[158:161], v[34:49]
	v_exp_f32_e32 v126, v66
	v_exp_f32_e32 v127, v67
	v_exp_f32_e32 v128, v68
	v_exp_f32_e32 v129, v69
	v_exp_f32_e32 v130, v70
	v_exp_f32_e32 v131, v71
	v_exp_f32_e32 v132, v72
	v_exp_f32_e32 v133, v73
	s_waitcnt lgkmcnt(1)
	v_mfma_f32_32x32x16_bf16 v[82:97], v[244:247], v[158:161], v[34:49]
	v_exp_f32_e32 v134, v74
	v_exp_f32_e32 v135, v75
	v_exp_f32_e32 v136, v76
	v_exp_f32_e32 v137, v77
	v_exp_f32_e32 v177, v78
	v_exp_f32_e32 v178, v79
	v_exp_f32_e32 v179, v80
	v_exp_f32_e32 v185, v81
	v_mfma_f32_32x32x16_bf16 v[138:153], v[106:109], v[154:157], v[138:153]
	v_exp_f32_e32 v80, v50
	v_exp_f32_e32 v81, v51
	v_exp_f32_e32 v186, v52
	v_exp_f32_e32 v187, v53
	v_exp_f32_e32 v194, v54
	v_exp_f32_e32 v195, v55
	v_exp_f32_e32 v196, v56
	v_exp_f32_e32 v197, v57
	s_waitcnt lgkmcnt(0)
	v_mfma_f32_32x32x16_bf16 v[82:97], v[122:125], v[154:157], v[82:97]
	v_exp_f32_e32 v198, v58
	v_exp_f32_e32 v199, v59
	v_exp_f32_e32 v200, v60
	v_exp_f32_e32 v201, v61
	v_exp_f32_e32 v122, v62
	v_exp_f32_e32 v123, v63
	v_exp_f32_e32 v124, v64
	v_exp_f32_e32 v125, v65
	s_cmp_gt_i32 s25, 2
	s_cselect_b32 s26, -3, 2
	s_add_i32 s26, s26, s25
	s_mulk_i32 s26, 0x2400
	v_add_u32_e32 v50, s26, v182
	s_add_i32 s26, s25, 1
	s_cmp_lg_u32 s25, 4
	s_cselect_b32 s25, s26, 0
	s_add_i32 s26, s23, -1
	s_min_u32 s26, s26, s13
	s_lshl_b32 s92, s26, 13
	s_waitcnt vmcnt(3)
	ds_write_b128 v182, v[118:121] offset:9216
	s_waitcnt vmcnt(2)
	ds_write_b128 v50, v[114:117] offset:36864
	s_add_u32 vcc_lo, s100, s92
	s_addc_u32 vcc_hi, s101, 0
	global_load_dwordx4 v[56:59], v248, vcc
	s_lshl_b32 s92, s27, 7
	s_add_u32 vcc_lo, s98, s92
	s_addc_u32 vcc_hi, s99, 0
	global_load_dwordx4 v[52:55], v249, vcc
	s_nop 0
	s_mul_i32 s27, s25, 0x2400
	s_add_i32 s28, s27, 0xffffdc00
	s_cmp_lg_u32 s25, 0
	s_cselect_b32 s28, s28, 0x9000
	v_add_u32_e32 v50, s28, v163
	ds_read_b128 v[60:63], v50 offset:36864
	ds_read_b128 v[64:67], v50 offset:36896
	ds_read_b128 v[68:71], v50 offset:41472
	ds_read_b128 v[72:75], v50 offset:41504
	ds_read_b128 v[76:79], v50 offset:36928
	ds_read_b128 v[106:109], v50 offset:36960
	ds_read_b128 v[110:113], v50 offset:41536
	ds_read_b128 v[114:117], v50 offset:41568
	s_setprio 3
	v_cvt_pk_bf16_f32 v118, v126, v127
	v_cvt_pk_bf16_f32 v119, v128, v129
	v_cvt_pk_bf16_f32 v120, v130, v131
	v_cvt_pk_bf16_f32 v121, v132, v133
	s_waitcnt lgkmcnt(7)
	s_nop 0
	v_mfma_f32_32x32x16_bf16 v[18:33], v[60:63], v[118:121], v[18:33]
	v_mov_b32_e32 v50, v126
	v_add_f32_e32 v50, v50, v127
	v_add_f32_e32 v50, v50, v128
	v_add_f32_e32 v50, v50, v129
	s_waitcnt lgkmcnt(5)
	v_mfma_f32_32x32x16_bf16 v[2:17], v[68:71], v[118:121], v[2:17]
	v_cvt_pk_bf16_f32 v60, v134, v135
	v_cvt_pk_bf16_f32 v61, v136, v137
	v_cvt_pk_bf16_f32 v62, v177, v178
	v_cvt_pk_bf16_f32 v63, v179, v185
	v_add_f32_e32 v50, v50, v130
	v_add_f32_e32 v50, v50, v131
	v_add_f32_e32 v50, v50, v132
	v_add_f32_e32 v50, v50, v133
	s_nop 0
	v_mfma_f32_32x32x16_bf16 v[18:33], v[64:67], v[60:63], v[18:33]
	v_add_f32_e32 v50, v50, v134
	v_add_f32_e32 v50, v50, v135
	v_add_f32_e32 v50, v50, v136
	v_add_f32_e32 v50, v50, v137
	s_waitcnt lgkmcnt(4)
	v_mfma_f32_32x32x16_bf16 v[2:17], v[72:75], v[60:63], v[2:17]
	v_cvt_pk_bf16_f32 v64, v80, v81
	v_cvt_pk_bf16_f32 v65, v186, v187
	v_cvt_pk_bf16_f32 v66, v194, v195
	v_cvt_pk_bf16_f32 v67, v196, v197
	v_add_f32_e32 v50, v50, v177
	v_add_f32_e32 v50, v50, v178
	v_add_f32_e32 v50, v50, v179
	v_add_f32_e32 v50, v50, v185
	s_waitcnt lgkmcnt(3)
	v_mfma_f32_32x32x16_bf16 v[18:33], v[76:79], v[64:67], v[18:33]
	v_add_f32_e32 v50, v50, v80
	v_add_f32_e32 v50, v50, v81
	v_add_f32_e32 v50, v50, v186
	v_add_f32_e32 v50, v50, v187
	s_waitcnt lgkmcnt(1)
	v_mfma_f32_32x32x16_bf16 v[2:17], v[110:113], v[64:67], v[2:17]
	v_cvt_pk_bf16_f32 v60, v198, v199
	v_cvt_pk_bf16_f32 v61, v200, v201
	v_cvt_pk_bf16_f32 v62, v122, v123
	v_cvt_pk_bf16_f32 v63, v124, v125
	v_add_f32_e32 v50, v50, v194
	v_add_f32_e32 v50, v50, v195
	v_add_f32_e32 v50, v50, v196
	v_add_f32_e32 v50, v50, v197
	s_nop 0
	v_mfma_f32_32x32x16_bf16 v[18:33], v[106:109], v[60:63], v[18:33]
	v_add_f32_e32 v50, v50, v198
	v_add_f32_e32 v50, v50, v199
	v_add_f32_e32 v50, v50, v200
	v_add_f32_e32 v50, v50, v201
	s_waitcnt lgkmcnt(0)
	v_mfma_f32_32x32x16_bf16 v[2:17], v[114:117], v[60:63], v[2:17]
	v_add_f32_e32 v50, v50, v122
	v_add_f32_e32 v50, v50, v123
	v_add_f32_e32 v50, v50, v124
	v_add_f32_e32 v50, v50, v125
	s_setprio 2
	s_waitcnt lgkmcnt(0)
	s_barrier
	ds_read_b128 v[240:243], v165
	ds_read_b128 v[244:247], v165 offset:4608
	ds_read_b128 v[68:71], v165 offset:32
	ds_read_b128 v[72:75], v165 offset:4640
	v_add_f32_e32 v1, v1, v176
	s_waitcnt lgkmcnt(2)
	v_mfma_f32_32x32x16_bf16 v[122:137], v[240:243], v[158:161], v[34:49]
	v_exp_f32_e32 v176, v138
	v_exp_f32_e32 v177, v139
	v_exp_f32_e32 v178, v140
	v_exp_f32_e32 v179, v141
	v_exp_f32_e32 v185, v142
	v_exp_f32_e32 v186, v143
	v_exp_f32_e32 v187, v144
	v_exp_f32_e32 v194, v145
	v_mfma_f32_32x32x16_bf16 v[106:121], v[244:247], v[158:161], v[34:49]
	v_exp_f32_e32 v195, v146
	v_exp_f32_e32 v196, v147
	v_exp_f32_e32 v197, v148
	v_exp_f32_e32 v198, v149
	v_exp_f32_e32 v146, v150
	v_exp_f32_e32 v147, v151
	v_exp_f32_e32 v148, v152
	v_exp_f32_e32 v149, v153
	s_waitcnt lgkmcnt(1)
	v_mfma_f32_32x32x16_bf16 v[122:137], v[68:71], v[154:157], v[122:137]
	v_exp_f32_e32 v150, v82
	v_exp_f32_e32 v151, v83
	v_exp_f32_e32 v152, v84
	v_exp_f32_e32 v153, v85
	v_exp_f32_e32 v199, v86
	v_exp_f32_e32 v200, v87
	v_exp_f32_e32 v201, v88
	v_exp_f32_e32 v202, v89
	s_waitcnt lgkmcnt(0)
	v_mfma_f32_32x32x16_bf16 v[106:121], v[72:75], v[154:157], v[106:121]
	v_exp_f32_e32 v203, v90
	v_exp_f32_e32 v204, v91
	v_exp_f32_e32 v205, v92
	v_exp_f32_e32 v206, v93
	v_exp_f32_e32 v207, v94
	v_exp_f32_e32 v208, v95
	v_exp_f32_e32 v209, v96
	v_exp_f32_e32 v210, v97
	s_cmp_gt_i32 s25, 2
	s_cselect_b32 s28, -3, 2
	s_add_i32 s28, s28, s25
	s_mulk_i32 s28, 0x2400
	v_add_u32_e32 v88, s27, v163
	s_min_u32 s27, s23, s13
	v_add_u32_e32 v51, s28, v182
	s_lshl_b32 s92, s27, 13
	s_waitcnt vmcnt(3)
	ds_write_b128 v182, v[98:101] offset:18432
	s_waitcnt vmcnt(2)
	ds_write_b128 v51, v[102:105] offset:36864
	v_add_f32_e32 v1, v1, v50
	s_add_u32 vcc_lo, s100, s92
	s_addc_u32 vcc_hi, s101, 0
	global_load_dwordx4 v[138:141], v248, vcc
	s_lshl_b32 s92, s26, 7
	s_add_u32 vcc_lo, s98, s92
	s_addc_u32 vcc_hi, s99, 0
	global_load_dwordx4 v[142:145], v249, vcc
	ds_read_b128 v[240:243], v165 offset:9216
	ds_read_b128 v[244:247], v165 offset:13824
	ds_read_b128 v[60:63], v88 offset:41472
	ds_read_b128 v[64:67], v88 offset:36864
	ds_read_b128 v[68:71], v88 offset:36896
	ds_read_b128 v[72:75], v88 offset:41504
	ds_read_b128 v[76:79], v88 offset:36928
	ds_read_b128 v[80:83], v88 offset:41536
	ds_read_b128 v[84:87], v88 offset:36960
	ds_read_b128 v[88:91], v88 offset:41568
	s_setprio 1
	v_mov_b32_e32 v51, v122
	v_cvt_pk_bf16_f32 v92, v176, v177
	v_cvt_pk_bf16_f32 v93, v178, v179
	v_cvt_pk_bf16_f32 v94, v185, v186
	v_cvt_pk_bf16_f32 v95, v187, v194
	s_waitcnt lgkmcnt(6)
	s_nop 0
	v_mfma_f32_32x32x16_bf16 v[18:33], v[64:67], v[92:95], v[18:33]
	v_max3_f32 v51, v51, v123, v124
	v_max3_f32 v51, v51, v125, v126
	v_mov_b32_e32 v50, v176
	v_add_f32_e32 v50, v50, v177
	v_add_f32_e32 v50, v50, v178
	v_add_f32_e32 v50, v50, v179
	s_nop 0
	v_mfma_f32_32x32x16_bf16 v[2:17], v[60:63], v[92:95], v[2:17]
	v_cvt_pk_bf16_f32 v64, v195, v196
	v_cvt_pk_bf16_f32 v65, v197, v198
	v_cvt_pk_bf16_f32 v66, v146, v147
	v_cvt_pk_bf16_f32 v67, v148, v149
	v_max3_f32 v51, v51, v127, v128
	v_max3_f32 v51, v51, v129, v130
	v_add_f32_e32 v50, v50, v185
	v_add_f32_e32 v50, v50, v186
	v_add_f32_e32 v50, v50, v187
	v_add_f32_e32 v50, v50, v194
	s_waitcnt lgkmcnt(5)
	v_mfma_f32_32x32x16_bf16 v[18:33], v[68:71], v[64:67], v[18:33]
	v_max3_f32 v51, v51, v131, v132
	v_max3_f32 v51, v51, v133, v134
	v_add_f32_e32 v50, v50, v195
	v_add_f32_e32 v50, v50, v196
	v_add_f32_e32 v50, v50, v197
	v_add_f32_e32 v50, v50, v198
	s_waitcnt lgkmcnt(4)
	v_mfma_f32_32x32x16_bf16 v[2:17], v[72:75], v[64:67], v[2:17]
	v_cvt_pk_bf16_f32 v60, v150, v151
	v_cvt_pk_bf16_f32 v61, v152, v153
	v_cvt_pk_bf16_f32 v62, v199, v200
	v_cvt_pk_bf16_f32 v63, v201, v202
	v_max3_f32 v51, v51, v135, v136
	v_max3_f32 v51, v51, v137, v106
	v_add_f32_e32 v50, v50, v146
	v_add_f32_e32 v50, v50, v147
	v_add_f32_e32 v50, v50, v148
	v_add_f32_e32 v50, v50, v149
	s_waitcnt lgkmcnt(3)
	v_mfma_f32_32x32x16_bf16 v[18:33], v[76:79], v[60:63], v[18:33]
	v_max3_f32 v51, v51, v107, v108
	v_max3_f32 v51, v51, v109, v110
	v_add_f32_e32 v50, v50, v150
	v_add_f32_e32 v50, v50, v151
	v_add_f32_e32 v50, v50, v152
	v_add_f32_e32 v50, v50, v153
	s_waitcnt lgkmcnt(2)
	v_mfma_f32_32x32x16_bf16 v[2:17], v[80:83], v[60:63], v[2:17]
	v_cvt_pk_bf16_f32 v64, v203, v204
	v_cvt_pk_bf16_f32 v65, v205, v206
	v_cvt_pk_bf16_f32 v66, v207, v208
	v_cvt_pk_bf16_f32 v67, v209, v210
	v_max3_f32 v51, v51, v111, v112
	v_max3_f32 v51, v51, v113, v114
	v_add_f32_e32 v50, v50, v199
	v_add_f32_e32 v50, v50, v200
	v_add_f32_e32 v50, v50, v201
	v_add_f32_e32 v50, v50, v202
	s_waitcnt lgkmcnt(1)
	v_mfma_f32_32x32x16_bf16 v[18:33], v[84:87], v[64:67], v[18:33]
	v_max3_f32 v51, v51, v115, v116
	v_max3_f32 v51, v51, v117, v118
	v_add_f32_e32 v50, v50, v203
	v_add_f32_e32 v50, v50, v204
	v_add_f32_e32 v50, v50, v205
	v_add_f32_e32 v50, v50, v206
	s_waitcnt lgkmcnt(0)
	v_mfma_f32_32x32x16_bf16 v[2:17], v[88:91], v[64:67], v[2:17]
	v_max3_f32 v51, v51, v119, v120
	v_max3_f32 v51, v51, v121, v121
	v_add_f32_e32 v50, v50, v207
	v_add_f32_e32 v50, v50, v208
	v_add_f32_e32 v50, v50, v209
	v_add_f32_e32 v50, v50, v210
	s_setprio 0
	ds_read_b128 v[146:149], v165 offset:9248
	ds_read_b128 v[60:63], v165 offset:13856
	v_add_f32_e32 v50, v1, v50
	v_mov_b32_e32 v1, v51
	s_nop 1
	v_permlane32_swap_b32_e32 v51, v1
	v_max_f32_e32 v1, v1, v1
	v_max_f32_e32 v51, v51, v51
	v_max_f32_e32 v1, v51, v1
	v_cmp_lt_f32_e32 vcc, s52, v1
	s_cbranch_vccz .LBB0_643
	v_max_f32_e32 v1, v1, v1
	v_max_f32_e32 v68, 0, v1
	v_add_f32_e32 v183, v183, v68
	v_xor_b32_e32 v34, 0x80000000, v183
	v_pk_add_f32 v[122:123], v[122:123], v[68:69] op_sel_hi:[1,0] neg_lo:[0,1] neg_hi:[0,1]
	v_pk_add_f32 v[106:107], v[106:107], v[68:69] op_sel_hi:[1,0] neg_lo:[0,1] neg_hi:[0,1]
	v_pk_add_f32 v[124:125], v[124:125], v[68:69] op_sel_hi:[1,0] neg_lo:[0,1] neg_hi:[0,1]
	v_pk_add_f32 v[108:109], v[108:109], v[68:69] op_sel_hi:[1,0] neg_lo:[0,1] neg_hi:[0,1]
	v_pk_add_f32 v[126:127], v[126:127], v[68:69] op_sel_hi:[1,0] neg_lo:[0,1] neg_hi:[0,1]
	v_pk_add_f32 v[110:111], v[110:111], v[68:69] op_sel_hi:[1,0] neg_lo:[0,1] neg_hi:[0,1]
	v_pk_add_f32 v[128:129], v[128:129], v[68:69] op_sel_hi:[1,0] neg_lo:[0,1] neg_hi:[0,1]
	v_pk_add_f32 v[112:113], v[112:113], v[68:69] op_sel_hi:[1,0] neg_lo:[0,1] neg_hi:[0,1]
	v_pk_add_f32 v[130:131], v[130:131], v[68:69] op_sel_hi:[1,0] neg_lo:[0,1] neg_hi:[0,1]
	v_pk_add_f32 v[114:115], v[114:115], v[68:69] op_sel_hi:[1,0] neg_lo:[0,1] neg_hi:[0,1]
	v_pk_add_f32 v[132:133], v[132:133], v[68:69] op_sel_hi:[1,0] neg_lo:[0,1] neg_hi:[0,1]
	v_pk_add_f32 v[116:117], v[116:117], v[68:69] op_sel_hi:[1,0] neg_lo:[0,1] neg_hi:[0,1]
	v_pk_add_f32 v[134:135], v[134:135], v[68:69] op_sel_hi:[1,0] neg_lo:[0,1] neg_hi:[0,1]
	v_pk_add_f32 v[118:119], v[118:119], v[68:69] op_sel_hi:[1,0] neg_lo:[0,1] neg_hi:[0,1]
	v_pk_add_f32 v[136:137], v[136:137], v[68:69] op_sel_hi:[1,0] neg_lo:[0,1] neg_hi:[0,1]
	v_pk_add_f32 v[120:121], v[120:121], v[68:69] op_sel_hi:[1,0] neg_lo:[0,1] neg_hi:[0,1]
	v_exp_f32_e64 v68, -v68
	v_mov_b32_e32 v35, v34
	v_mov_b32_e32 v36, v34
	v_mov_b32_e32 v37, v34
	v_mov_b32_e32 v38, v34
	v_mov_b32_e32 v39, v34
	v_mov_b32_e32 v40, v34
	v_mov_b32_e32 v41, v34
	v_mov_b32_e32 v42, v34
	v_mov_b32_e32 v43, v34
	v_mov_b32_e32 v44, v34
	v_mov_b32_e32 v45, v34
	v_mov_b32_e32 v46, v34
	v_mov_b32_e32 v47, v34
	v_mov_b32_e32 v48, v34
	v_mov_b32_e32 v49, v34
	s_nop 11
	v_pk_mul_f32 v[32:33], v[32:33], v[68:69] op_sel_hi:[1,0]
	v_pk_mul_f32 v[30:31], v[30:31], v[68:69] op_sel_hi:[1,0]
	v_pk_mul_f32 v[28:29], v[28:29], v[68:69] op_sel_hi:[1,0]
	v_pk_mul_f32 v[26:27], v[26:27], v[68:69] op_sel_hi:[1,0]
	v_pk_mul_f32 v[24:25], v[24:25], v[68:69] op_sel_hi:[1,0]
	v_pk_mul_f32 v[22:23], v[22:23], v[68:69] op_sel_hi:[1,0]
	v_pk_mul_f32 v[20:21], v[20:21], v[68:69] op_sel_hi:[1,0]
	v_pk_mul_f32 v[18:19], v[18:19], v[68:69] op_sel_hi:[1,0]
	v_pk_mul_f32 v[16:17], v[16:17], v[68:69] op_sel_hi:[1,0]
	v_pk_mul_f32 v[14:15], v[14:15], v[68:69] op_sel_hi:[1,0]
	v_pk_mul_f32 v[12:13], v[12:13], v[68:69] op_sel_hi:[1,0]
	v_pk_mul_f32 v[10:11], v[10:11], v[68:69] op_sel_hi:[1,0]
	v_pk_mul_f32 v[8:9], v[8:9], v[68:69] op_sel_hi:[1,0]
	v_pk_mul_f32 v[6:7], v[6:7], v[68:69] op_sel_hi:[1,0]
	v_pk_mul_f32 v[4:5], v[4:5], v[68:69] op_sel_hi:[1,0]
	v_pk_mul_f32 v[2:3], v[2:3], v[68:69] op_sel_hi:[1,0]
	v_mul_f32_e32 v50, v50, v68

.LBB0_658:
	s_lshl_b32 s1, s0, 1
	s_xor_b64 s[26:27], s[12:13], -1
	s_lshl_b32 s63, s73, 7
	s_add_i32 s19, s1, s74
	s_lshl_b32 s23, s74, 1
	s_lshl_b32 s24, s0, 2
	s_ashr_i32 s22, s63, 31
	s_mul_hi_u32 s18, s19, 0x208000
	s_mul_i32 s19, s19, 0x208000
	s_mov_b64 s[12:13], -1
	s_and_b64 vcc, exec, s[26:27]
	s_cbranch_vccz .LBB0_694
	v_mov_b32_e32 v76, v222
	v_mov_b32_e32 v53, v0
	v_readfirstlane_b32 s1, v76
	s_ashr_i32 s25, s1, 8
	s_add_i32 s25, s25, s23
	s_lshr_b32 s1, s1, 1
	s_add_i32 s2, s25, s24
	s_and_b32 s1, s1, 0x60
	s_mul_hi_i32 s12, s2, 0x4100
	s_mulk_i32 s2, 0x4100
	s_add_u32 s2, s2, s63
	v_and_b32_e32 v207, 31, v76
	s_addc_u32 s12, s12, s22
	s_or_b32 s2, s2, s1
	v_or_b32_e32 v2, s2, v207
	v_mov_b32_e32 v3, s12
	v_bfe_u32 v206, v76, 5, 1
	v_lshlrev_b64 v[2:3], 7, v[2:3]
	v_lshl_add_u64 v[2:3], s[14:15], 0, v[2:3]
	v_lshlrev_b32_e32 v52, 4, v206
	s_add_u32 s12, s40, s19
	v_lshl_add_u64 v[2:3], v[2:3], 0, v[52:53]
	s_addc_u32 s13, s41, s18
	v_ashrrev_i32_e32 v74, 3, v76
	global_load_dwordx4 v[180:183], v[2:3], off
	global_load_dwordx4 v[176:179], v[2:3], off offset:32
	global_load_dwordx4 v[172:175], v[2:3], off offset:64
	global_load_dwordx4 v[168:171], v[2:3], off offset:96
	s_add_u32 s26, s38, s19
	v_ashrrev_i32_e32 v75, 31, v74
	v_mov_b64_e32 v[2:3], s[12:13]
	v_lshlrev_b32_e32 v1, 4, v76
	s_addc_u32 s27, s39, s18
	v_lshlrev_b64 v[72:73], 7, v[74:75]
	v_mad_i64_i32 v[2:3], s[12:13], v74, s55, v[2:3]
	v_and_b32_e32 v54, 0x70, v1
	v_mov_b32_e32 v55, v0
	v_lshl_add_u64 v[196:197], v[2:3], 0, v[54:55]
	v_lshl_add_u64 v[2:3], s[26:27], 0, v[72:73]
	v_lshl_add_u64 v[198:199], v[2:3], 0, v[54:55]
	s_nop 1
	v_readfirstlane_b32 s100, v198
	v_readfirstlane_b32 s101, v199
	v_readfirstlane_b32 s98, v196
	v_readfirstlane_b32 s99, v197
	s_nop 1
	v_subrev_u32_e32 v248, s100, v198
	v_subrev_u32_e32 v249, s98, v196
	v_add_co_u32_e32 v44, vcc, s3, v198
	v_mov_b32_e32 v14, v0
	v_mov_b32_e32 v15, v0
	v_addc_co_u32_e32 v45, vcc, 0, v199, vcc
	v_mov_b32_e32 v1, v0
	v_mov_b32_e32 v2, v0
	v_mov_b32_e32 v3, v0
	v_mov_b32_e32 v4, v0
	v_mov_b32_e32 v5, v0
	v_mov_b32_e32 v6, v0
	v_mov_b32_e32 v7, v0
	v_mov_b32_e32 v8, v0
	v_mov_b32_e32 v9, v0
	v_mov_b32_e32 v10, v0
	v_mov_b32_e32 v11, v0
	v_mov_b32_e32 v12, v0
	v_mov_b32_e32 v13, v0
	v_mov_b64_e32 v[30:31], v[14:15]
	v_add_co_u32_e32 v48, vcc, s59, v198
	v_mov_b64_e32 v[28:29], v[12:13]
	v_mov_b64_e32 v[26:27], v[10:11]
	v_mov_b64_e32 v[24:25], v[8:9]
	v_mov_b64_e32 v[22:23], v[6:7]
	v_mov_b64_e32 v[20:21], v[4:5]
	v_mov_b64_e32 v[18:19], v[2:3]
	v_mov_b64_e32 v[16:17], v[0:1]
	v_addc_co_u32_e32 v49, vcc, 0, v199, vcc
	global_load_dwordx4 v[32:35], v[198:199], off
	global_load_dwordx4 v[36:39], v[196:197], off
	global_load_dwordx4 v[40:43], v[196:197], off offset:128
	s_nop 0
	global_load_dwordx4 v[44:47], v[44:45], off
	s_nop 0
	global_load_dwordx4 v[48:51], v[48:49], off
	v_mul_u32_u24_e32 v53, 0x90, v207
	v_mad_u64_u32 v[194:195], s[12:13], v74, s60, v[54:55]
	v_add3_u32 v195, 0, v53, v52
	v_add_co_u32_e32 v52, vcc, s33, v198
	v_add_u32_e32 v208, 0, v194
	s_nop 0
	v_addc_co_u32_e32 v53, vcc, 0, v199, vcc
	global_load_dwordx4 v[64:67], v[196:197], off offset:256
	global_load_dwordx4 v[68:71], v[52:53], off
	s_cmp_gt_i32 s73, 1
	s_cselect_b32 s92, 0x8000, s33
	s_cselect_b32 s2, 0x104, 4
	s_mov_b32 s27, 1
	s_add_i32 s12, s2, -1
	s_cmp_lt_i32 s73, 2
	s_barrier
	s_waitcnt vmcnt(5)
	ds_write_b128 v208, v[36:39] offset:36864
	s_waitcnt vmcnt(4)
	ds_write_b128 v208, v[40:43] offset:46080
	ds_write_b128 v208, v[32:35]
	s_waitcnt vmcnt(3)
	ds_write_b128 v208, v[44:47] offset:9216
	s_waitcnt vmcnt(2)
	ds_write_b128 v208, v[48:51] offset:18432
	s_waitcnt lgkmcnt(0)
	s_barrier
	ds_read_b128 v[48:51], v195
	ds_read_b128 v[52:55], v195 offset:4608
	s_waitcnt lgkmcnt(1)
	v_mfma_f32_32x32x16_bf16 v[32:47], v[48:51], v[180:183], v[16:31]
	v_lshl_add_u64 v[48:49], v[198:199], 0, s[92:93]
	global_load_dwordx4 v[152:155], v[48:49], off
	global_load_dwordx4 v[156:159], v[196:197], off offset:384
	ds_read_b128 v[48:51], v195 offset:32
	s_waitcnt lgkmcnt(0)
	v_mfma_f32_32x32x16_bf16 v[32:47], v[48:51], v[176:179], v[32:47]
	ds_read_b128 v[48:51], v195 offset:4640
	v_mfma_f32_32x32x16_bf16 v[16:31], v[52:55], v[180:183], v[16:31]
	s_waitcnt lgkmcnt(0)
	v_mfma_f32_32x32x16_bf16 v[16:31], v[48:51], v[176:179], v[16:31]
	ds_read_b128 v[48:51], v195 offset:64
	s_waitcnt lgkmcnt(0)
	v_mfma_f32_32x32x16_bf16 v[32:47], v[48:51], v[172:175], v[32:47]
	ds_read_b128 v[48:51], v195 offset:4672
	s_waitcnt lgkmcnt(0)
	v_mfma_f32_32x32x16_bf16 v[16:31], v[48:51], v[172:175], v[16:31]
	ds_read_b128 v[48:51], v195 offset:96
	s_waitcnt lgkmcnt(0)
	v_mfma_f32_32x32x16_bf16 v[32:47], v[48:51], v[168:171], v[32:47]
	ds_read_b128 v[48:51], v195 offset:4704
	s_waitcnt lgkmcnt(0)
	v_mfma_f32_32x32x16_bf16 v[16:31], v[48:51], v[168:171], v[16:31]
	v_max3_f32 v48, v32, v33, v34
	s_nop 0
	v_max3_f32 v48, v48, v35, v36
	s_nop 0
	v_max3_f32 v48, v48, v37, v38
	s_nop 0
	v_max3_f32 v48, v48, v39, v40
	s_nop 0
	v_max3_f32 v48, v48, v41, v42
	s_nop 0
	v_max3_f32 v48, v48, v43, v44
	s_nop 0
	v_max3_f32 v48, v48, v45, v46
	s_nop 0
	v_max3_f32 v48, v48, v47, v16
	s_nop 0
	v_max3_f32 v48, v48, v17, v18
	s_nop 0
	v_max3_f32 v48, v48, v19, v20
	s_nop 0
	v_max3_f32 v48, v48, v21, v22
	s_nop 0
	v_max3_f32 v48, v48, v23, v24
	s_nop 0
	v_max3_f32 v48, v48, v25, v26
	s_nop 0
	v_max3_f32 v48, v48, v27, v28
	s_nop 0
	v_max3_f32 v48, v48, v29, v30
	s_nop 0
	v_max3_f32 v48, v48, v31, v31
	s_setprio 0
	ds_read_b128 v[78:81], v195 offset:9216
	ds_read_b128 v[120:123], v195 offset:9248
	ds_read_b128 v[124:127], v195 offset:13824
	ds_read_b128 v[128:131], v195 offset:13856
	ds_read_b128 v[132:135], v195 offset:9280
	ds_read_b128 v[148:151], v195 offset:9312
	ds_read_b128 v[160:163], v195 offset:13888
	ds_read_b128 v[164:167], v195 offset:13920
	v_mov_b32_e32 v49, v48
	s_nop 1
	v_permlane32_swap_b32_e32 v48, v49
	v_max_f32_e32 v49, v49, v49
	v_max_f32_e32 v48, v48, v48
	v_max_f32_e32 v49, v48, v49
	v_add_f32_e32 v209, 0, v49
	v_xor_b32_e32 v48, 0x80000000, v209
	v_sub_f32_e32 v32, v32, v49
	v_sub_f32_e32 v16, v16, v49
	v_sub_f32_e32 v33, v33, v49
	v_sub_f32_e32 v17, v17, v49
	v_sub_f32_e32 v34, v34, v49
	v_sub_f32_e32 v18, v18, v49
	v_sub_f32_e32 v35, v35, v49
	v_sub_f32_e32 v19, v19, v49
	v_sub_f32_e32 v36, v36, v49
	v_sub_f32_e32 v20, v20, v49
	v_sub_f32_e32 v37, v37, v49
	v_sub_f32_e32 v21, v21, v49
	v_sub_f32_e32 v38, v38, v49
	v_sub_f32_e32 v22, v22, v49
	v_sub_f32_e32 v39, v39, v49
	v_sub_f32_e32 v23, v23, v49
	v_sub_f32_e32 v40, v40, v49
	v_sub_f32_e32 v24, v24, v49
	v_sub_f32_e32 v41, v41, v49
	v_sub_f32_e32 v25, v25, v49
	v_sub_f32_e32 v42, v42, v49
	v_sub_f32_e32 v26, v26, v49
	v_sub_f32_e32 v43, v43, v49
	v_sub_f32_e32 v27, v27, v49
	v_sub_f32_e32 v44, v44, v49
	v_sub_f32_e32 v28, v28, v49
	v_sub_f32_e32 v45, v45, v49
	v_sub_f32_e32 v29, v29, v49
	v_sub_f32_e32 v46, v46, v49
	v_sub_f32_e32 v30, v30, v49
	v_sub_f32_e32 v47, v47, v49
	v_sub_f32_e32 v31, v31, v49
	v_mov_b32_e32 v49, v48
	v_mov_b32_e32 v50, v48
	v_mov_b32_e32 v51, v48
	v_mov_b32_e32 v52, v48
	v_mov_b32_e32 v53, v48
	v_mov_b32_e32 v54, v48
	v_mov_b32_e32 v55, v48
	v_mov_b32_e32 v56, v48
	v_mov_b32_e32 v57, v48
	v_mov_b32_e32 v58, v48
	v_mov_b32_e32 v59, v48
	v_mov_b32_e32 v60, v48
	v_mov_b32_e32 v61, v48
	v_mov_b32_e32 v62, v48
	v_mov_b32_e32 v63, v48
	s_waitcnt lgkmcnt(7)
	s_nop 4
	v_mfma_f32_32x32x16_bf16 v[96:111], v[78:81], v[180:183], v[48:63]
	v_exp_f32_e32 v116, v32
	v_exp_f32_e32 v117, v33
	v_exp_f32_e32 v118, v34
	v_exp_f32_e32 v119, v35
	s_nop 0
	s_waitcnt lgkmcnt(5)
	s_nop 4
	v_mfma_f32_32x32x16_bf16 v[80:95], v[124:127], v[180:183], v[48:63]
	v_exp_f32_e32 v112, v36
	v_exp_f32_e32 v113, v37
	v_exp_f32_e32 v114, v38
	v_exp_f32_e32 v115, v39
	s_nop 0
	v_mfma_f32_32x32x16_bf16 v[96:111], v[120:123], v[176:179], v[96:111]
	v_exp_f32_e32 v187, v40
	v_exp_f32_e32 v186, v41
	v_exp_f32_e32 v185, v42
	v_exp_f32_e32 v184, v43
	s_nop 0
	s_waitcnt lgkmcnt(4)
	v_mfma_f32_32x32x16_bf16 v[80:95], v[128:131], v[176:179], v[80:95]
	v_exp_f32_e32 v147, v44
	v_exp_f32_e32 v146, v45
	v_exp_f32_e32 v145, v46
	v_exp_f32_e32 v144, v47
	s_nop 0
	s_waitcnt lgkmcnt(3)
	v_mfma_f32_32x32x16_bf16 v[96:111], v[132:135], v[172:175], v[96:111]
	v_exp_f32_e32 v143, v16
	v_exp_f32_e32 v142, v17
	v_exp_f32_e32 v141, v18
	v_exp_f32_e32 v140, v19
	s_nop 0
	s_waitcnt lgkmcnt(1)
	v_mfma_f32_32x32x16_bf16 v[80:95], v[160:163], v[172:175], v[80:95]
	v_exp_f32_e32 v139, v20
	v_exp_f32_e32 v138, v21
	v_exp_f32_e32 v137, v22
	v_exp_f32_e32 v136, v23
	s_nop 0
	v_mfma_f32_32x32x16_bf16 v[96:111], v[148:151], v[168:171], v[96:111]
	v_exp_f32_e32 v123, v24
	v_exp_f32_e32 v122, v25
	v_exp_f32_e32 v121, v26
	v_exp_f32_e32 v120, v27
	s_nop 0
	s_waitcnt lgkmcnt(0)
	v_mfma_f32_32x32x16_bf16 v[80:95], v[164:167], v[168:171], v[80:95]
	v_exp_f32_e32 v127, v28
	v_exp_f32_e32 v126, v29
	v_exp_f32_e32 v125, v30
	v_exp_f32_e32 v124, v31
	s_nop 0
	s_waitcnt vmcnt(2)
	ds_write_b128 v208, v[68:71] offset:27648
	ds_write_b128 v208, v[64:67] offset:55296
	s_cbranch_scc1 .LBB0_681
	v_mad_i64_i32 v[16:17], s[26:27], v74, s55, 0
	s_add_u32 s26, s4, s19
	v_and_b32_e32 v18, 7, v76
	s_addc_u32 s27, s5, s18
	v_lshlrev_b32_e32 v200, 4, v18
	v_lshl_add_u64 v[202:203], s[26:27], 0, v[16:17]
	v_mov_b64_e32 v[30:31], v[14:15]
	v_mov_b64_e32 v[46:47], v[14:15]
	v_mov_b32_e32 v201, v0
	v_lshl_add_u64 v[204:205], s[26:27], 0, v[72:73]
	s_mov_b32 s27, 1
	v_mov_b32_e32 v64, 0
	s_mov_b32 s13, 12
	v_mov_b64_e32 v[28:29], v[12:13]
	v_mov_b64_e32 v[26:27], v[10:11]
	v_mov_b64_e32 v[24:25], v[8:9]
	v_mov_b64_e32 v[22:23], v[6:7]
	v_mov_b64_e32 v[20:21], v[4:5]
	v_mov_b64_e32 v[18:19], v[2:3]
	v_mov_b64_e32 v[16:17], v[0:1]
	v_mov_b64_e32 v[44:45], v[12:13]
	v_mov_b64_e32 v[42:43], v[10:11]
	v_mov_b64_e32 v[40:41], v[8:9]
	v_mov_b64_e32 v[38:39], v[6:7]
	v_mov_b64_e32 v[36:37], v[4:5]
	v_mov_b64_e32 v[34:35], v[2:3]
	v_mov_b64_e32 v[32:33], v[0:1]
.LBB0_661:
	v_lshl_add_u64 v[164:165], v[204:205], 0, v[200:201]
	s_mov_b32 s26, 0x1da8a000
	v_add_co_u32_e32 v2, vcc, s26, v164
	v_lshl_add_u64 v[6:7], v[202:203], 0, v[200:201]
	s_nop 0
	v_addc_co_u32_e32 v3, vcc, 0, v165, vcc
	s_mov_b32 s26, 0x1e2a0000
	v_add_co_u32_e32 v14, vcc, s26, v6
	s_nop 0
	v_addc_co_u32_e32 v15, vcc, 0, v7, vcc
	global_load_dwordx4 v[2:5], v[2:3], off
	s_mul_i32 s28, s27, 0x2400
	global_load_dwordx4 v[6:9], v[14:15], off offset:512
	s_add_i32 s26, s13, -7
	s_add_i32 s29, s28, 0xffffdc00
	s_cmp_lg_u32 s27, 0
	s_cselect_b32 s29, s29, 0x9000
	v_add_u32_e32 v1, s29, v195
	ds_read_b128 v[10:13], v1 offset:36864
	ds_read_b128 v[66:69], v1 offset:36896
	ds_read_b128 v[70:73], v1 offset:41472
	ds_read_b128 v[74:77], v1 offset:41504
	ds_read_b128 v[128:131], v1 offset:36928
	ds_read_b128 v[132:135], v1 offset:36960
	ds_read_b128 v[148:151], v1 offset:41536
	ds_read_b128 v[160:163], v1 offset:41568
	s_setprio 3
	v_cvt_pk_bf16_f32 v210, v116, v117
	v_cvt_pk_bf16_f32 v211, v118, v119
	v_cvt_pk_bf16_f32 v212, v112, v113
	v_cvt_pk_bf16_f32 v213, v114, v115
	s_waitcnt lgkmcnt(7)
	s_nop 0
	v_mfma_f32_32x32x16_bf16 v[16:31], v[10:13], v[210:213], v[16:31]
	v_mov_b32_e32 v1, v116
	v_add_f32_e32 v1, v1, v117
	v_add_f32_e32 v1, v1, v118
	v_add_f32_e32 v1, v1, v119
	s_waitcnt lgkmcnt(5)
	v_mfma_f32_32x32x16_bf16 v[32:47], v[70:73], v[210:213], v[32:47]
	v_cvt_pk_bf16_f32 v10, v187, v186
	v_cvt_pk_bf16_f32 v11, v185, v184
	v_cvt_pk_bf16_f32 v12, v147, v146
	v_cvt_pk_bf16_f32 v13, v145, v144
	v_add_f32_e32 v1, v1, v112
	v_add_f32_e32 v1, v1, v113
	v_add_f32_e32 v1, v1, v114
	v_add_f32_e32 v1, v1, v115
	s_nop 0
	v_mfma_f32_32x32x16_bf16 v[16:31], v[66:69], v[10:13], v[16:31]
	v_add_f32_e32 v1, v1, v187
	v_add_f32_e32 v1, v1, v186
	v_add_f32_e32 v1, v1, v185
	v_add_f32_e32 v1, v1, v184
	s_waitcnt lgkmcnt(4)
	v_mfma_f32_32x32x16_bf16 v[32:47], v[74:77], v[10:13], v[32:47]
	v_cvt_pk_bf16_f32 v66, v143, v142
	v_cvt_pk_bf16_f32 v67, v141, v140
	v_cvt_pk_bf16_f32 v68, v139, v138
	v_cvt_pk_bf16_f32 v69, v137, v136
	v_add_f32_e32 v1, v1, v147
	v_add_f32_e32 v1, v1, v146
	v_add_f32_e32 v1, v1, v145
	v_add_f32_e32 v1, v1, v144
	s_waitcnt lgkmcnt(3)
	v_mfma_f32_32x32x16_bf16 v[16:31], v[128:131], v[66:69], v[16:31]
	v_add_f32_e32 v1, v1, v143
	v_add_f32_e32 v1, v1, v142
	v_add_f32_e32 v1, v1, v141
	v_add_f32_e32 v1, v1, v140
	s_waitcnt lgkmcnt(1)
	v_mfma_f32_32x32x16_bf16 v[32:47], v[148:151], v[66:69], v[32:47]
	v_cvt_pk_bf16_f32 v10, v123, v122
	v_cvt_pk_bf16_f32 v11, v121, v120
	v_cvt_pk_bf16_f32 v12, v127, v126
	v_cvt_pk_bf16_f32 v13, v125, v124
	v_add_f32_e32 v1, v1, v139
	v_add_f32_e32 v1, v1, v138
	v_add_f32_e32 v1, v1, v137
	v_add_f32_e32 v1, v1, v136
	s_nop 0
	v_mfma_f32_32x32x16_bf16 v[16:31], v[132:135], v[10:13], v[16:31]
	v_add_f32_e32 v1, v1, v123
	v_add_f32_e32 v1, v1, v122
	v_add_f32_e32 v1, v1, v121
	v_add_f32_e32 v1, v1, v120
	s_waitcnt lgkmcnt(0)
	v_mfma_f32_32x32x16_bf16 v[32:47], v[160:163], v[10:13], v[32:47]
	v_add_f32_e32 v1, v1, v127
	v_add_f32_e32 v1, v1, v126
	v_add_f32_e32 v1, v1, v125
	v_add_f32_e32 v1, v1, v124
	s_setprio 2
	s_waitcnt lgkmcnt(0)
	s_barrier
	ds_read_b128 v[240:243], v195 offset:18432
	ds_read_b128 v[244:247], v195 offset:23040
	ds_read_b128 v[66:69], v195 offset:18464
	ds_read_b128 v[74:77], v195 offset:23072
	ds_read_b128 v[144:147], v195 offset:18496
	ds_read_b128 v[148:151], v195 offset:18528
	ds_read_b128 v[160:163], v195 offset:23104
	ds_read_b128 v[184:187], v195 offset:23136
	s_waitcnt lgkmcnt(6)
	v_mfma_f32_32x32x16_bf16 v[128:143], v[240:243], v[180:183], v[48:63]
	v_exp_f32_e32 v166, v96
	v_exp_f32_e32 v167, v97
	v_exp_f32_e32 v210, v98
	v_exp_f32_e32 v211, v99
	s_waitcnt lgkmcnt(5)
	v_mfma_f32_32x32x16_bf16 v[112:127], v[244:247], v[180:183], v[48:63]
	v_exp_f32_e32 v212, v100
	v_exp_f32_e32 v213, v101
	v_exp_f32_e32 v214, v102
	v_exp_f32_e32 v215, v103
	v_mfma_f32_32x32x16_bf16 v[128:143], v[66:69], v[176:179], v[128:143]
	v_exp_f32_e32 v100, v104
	v_exp_f32_e32 v101, v105
	v_exp_f32_e32 v102, v106
	v_exp_f32_e32 v103, v107
	s_waitcnt lgkmcnt(4)
	v_mfma_f32_32x32x16_bf16 v[112:127], v[74:77], v[176:179], v[112:127]
	v_exp_f32_e32 v104, v108
	v_exp_f32_e32 v105, v109
	v_exp_f32_e32 v106, v110
	v_exp_f32_e32 v107, v111
	s_waitcnt lgkmcnt(3)
	v_mfma_f32_32x32x16_bf16 v[128:143], v[144:147], v[172:175], v[128:143]
	v_exp_f32_e32 v108, v80
	v_exp_f32_e32 v109, v81
	v_exp_f32_e32 v110, v82
	v_exp_f32_e32 v111, v83
	s_waitcnt lgkmcnt(1)
	v_mfma_f32_32x32x16_bf16 v[112:127], v[160:163], v[172:175], v[112:127]
	v_exp_f32_e32 v144, v84
	v_exp_f32_e32 v145, v85
	v_exp_f32_e32 v146, v86
	v_exp_f32_e32 v147, v87
	v_mfma_f32_32x32x16_bf16 v[128:143], v[148:151], v[168:171], v[128:143]
	v_exp_f32_e32 v216, v88
	v_exp_f32_e32 v217, v89
	v_exp_f32_e32 v218, v90
	v_exp_f32_e32 v219, v91
	s_waitcnt lgkmcnt(0)
	v_mfma_f32_32x32x16_bf16 v[112:127], v[184:187], v[168:171], v[112:127]
	v_exp_f32_e32 v148, v92
	v_exp_f32_e32 v149, v93
	v_exp_f32_e32 v150, v94
	v_exp_f32_e32 v151, v95
	s_cmp_gt_i32 s27, 2
	s_cselect_b32 s29, -3, 2
	s_add_i32 s29, s29, s27
	v_add_u32_e32 v92, s28, v195
	s_add_i32 s28, s13, -6
	s_mulk_i32 s29, 0x2400
	s_min_u32 s28, s28, s12
	v_add_u32_e32 v10, s29, v208
	s_min_u32 s26, s26, s12
	s_lshl_b32 s92, s28, 13
	s_waitcnt vmcnt(3)
	ds_write_b128 v208, v[152:155]
	s_waitcnt vmcnt(2)
	ds_write_b128 v10, v[156:159] offset:36864
	s_add_u32 vcc_lo, s100, s92
	s_addc_u32 vcc_hi, s101, 0
	global_load_dwordx4 v[10:13], v248, vcc
	s_lshl_b32 s92, s26, 7
	v_add_f32_e32 v1, v64, v1
	s_add_u32 vcc_lo, s98, s92
	s_addc_u32 vcc_hi, s99, 0
	global_load_dwordx4 v[160:163], v249, vcc
	s_add_i32 s29, s27, 1
	ds_read_b128 v[240:243], v195 offset:27648
	ds_read_b128 v[244:247], v195 offset:32256
	ds_read_b128 v[64:67], v92 offset:41472
	ds_read_b128 v[68:71], v92 offset:36864
	ds_read_b128 v[72:75], v92 offset:36896
	ds_read_b128 v[76:79], v92 offset:41504
	ds_read_b128 v[80:83], v92 offset:36928
	ds_read_b128 v[84:87], v92 offset:41536
	ds_read_b128 v[88:91], v92 offset:36960
	ds_read_b128 v[92:95], v92 offset:41568
	s_setprio 1
	v_cvt_pk_bf16_f32 v96, v166, v167
	v_cvt_pk_bf16_f32 v97, v210, v211
	v_cvt_pk_bf16_f32 v98, v212, v213
	v_cvt_pk_bf16_f32 v99, v214, v215
	s_waitcnt lgkmcnt(6)
	s_nop 0
	v_mfma_f32_32x32x16_bf16 v[16:31], v[68:71], v[96:99], v[16:31]
	v_mov_b32_e32 v184, v166
	v_add_f32_e32 v184, v184, v167
	v_add_f32_e32 v184, v184, v210
	v_add_f32_e32 v184, v184, v211
	s_nop 0
	v_mfma_f32_32x32x16_bf16 v[32:47], v[64:67], v[96:99], v[32:47]
	v_cvt_pk_bf16_f32 v68, v100, v101
	v_cvt_pk_bf16_f32 v69, v102, v103
	v_cvt_pk_bf16_f32 v70, v104, v105
	v_cvt_pk_bf16_f32 v71, v106, v107
	v_add_f32_e32 v184, v184, v212
	v_add_f32_e32 v184, v184, v213
	v_add_f32_e32 v184, v184, v214
	v_add_f32_e32 v184, v184, v215
	s_waitcnt lgkmcnt(5)
	v_mfma_f32_32x32x16_bf16 v[16:31], v[72:75], v[68:71], v[16:31]
	v_add_f32_e32 v184, v184, v100
	v_add_f32_e32 v184, v184, v101
	v_add_f32_e32 v184, v184, v102
	v_add_f32_e32 v184, v184, v103
	s_waitcnt lgkmcnt(4)
	v_mfma_f32_32x32x16_bf16 v[32:47], v[76:79], v[68:71], v[32:47]
	v_cvt_pk_bf16_f32 v64, v108, v109
	v_cvt_pk_bf16_f32 v65, v110, v111
	v_cvt_pk_bf16_f32 v66, v144, v145
	v_cvt_pk_bf16_f32 v67, v146, v147
	v_add_f32_e32 v184, v184, v104
	v_add_f32_e32 v184, v184, v105
	v_add_f32_e32 v184, v184, v106
	v_add_f32_e32 v184, v184, v107
	s_waitcnt lgkmcnt(3)
	v_mfma_f32_32x32x16_bf16 v[16:31], v[80:83], v[64:67], v[16:31]
	v_add_f32_e32 v184, v184, v108
	v_add_f32_e32 v184, v184, v109
	v_add_f32_e32 v184, v184, v110
	v_add_f32_e32 v184, v184, v111
	s_waitcnt lgkmcnt(2)
	v_mfma_f32_32x32x16_bf16 v[32:47], v[84:87], v[64:67], v[32:47]
	v_cvt_pk_bf16_f32 v68, v216, v217
	v_cvt_pk_bf16_f32 v69, v218, v219
	v_cvt_pk_bf16_f32 v70, v148, v149
	v_cvt_pk_bf16_f32 v71, v150, v151
	v_add_f32_e32 v184, v184, v144
	v_add_f32_e32 v184, v184, v145
	v_add_f32_e32 v184, v184, v146
	v_add_f32_e32 v184, v184, v147
	s_waitcnt lgkmcnt(1)
	v_mfma_f32_32x32x16_bf16 v[16:31], v[88:91], v[68:71], v[16:31]
	v_add_f32_e32 v184, v184, v216
	v_add_f32_e32 v184, v184, v217
	v_add_f32_e32 v184, v184, v218
	v_add_f32_e32 v184, v184, v219
	s_waitcnt lgkmcnt(0)
	v_mfma_f32_32x32x16_bf16 v[32:47], v[92:95], v[68:71], v[32:47]
	v_add_f32_e32 v184, v184, v148
	v_add_f32_e32 v184, v184, v149
	v_add_f32_e32 v184, v184, v150
	v_add_f32_e32 v184, v184, v151
	s_setprio 0
	ds_read_b128 v[68:71], v195 offset:27680
	ds_read_b128 v[76:79], v195 offset:32288
	ds_read_b128 v[80:83], v195 offset:27712
	ds_read_b128 v[84:87], v195 offset:27744
	ds_read_b128 v[88:91], v195 offset:32320
	ds_read_b128 v[92:95], v195 offset:32352
	s_cmp_lg_u32 s27, 4
	s_cselect_b32 s26, s29, 0
	s_waitcnt lgkmcnt(6)
	v_mfma_f32_32x32x16_bf16 v[144:159], v[240:243], v[180:183], v[48:63]
	v_exp_f32_e32 v166, v128
	v_exp_f32_e32 v167, v129
	v_exp_f32_e32 v185, v130
	v_exp_f32_e32 v186, v131
	s_waitcnt lgkmcnt(5)
	v_mfma_f32_32x32x16_bf16 v[96:111], v[244:247], v[180:183], v[48:63]
	v_exp_f32_e32 v128, v132
	v_exp_f32_e32 v129, v133
	v_exp_f32_e32 v130, v134
	v_exp_f32_e32 v131, v135
	v_mfma_f32_32x32x16_bf16 v[144:159], v[68:71], v[176:179], v[144:159]
	v_exp_f32_e32 v132, v136
	v_exp_f32_e32 v133, v137
	v_exp_f32_e32 v134, v138
	v_exp_f32_e32 v135, v139
	s_waitcnt lgkmcnt(4)
	v_mfma_f32_32x32x16_bf16 v[96:111], v[76:79], v[176:179], v[96:111]
	v_exp_f32_e32 v136, v140
	v_exp_f32_e32 v137, v141
	v_exp_f32_e32 v138, v142
	v_exp_f32_e32 v139, v143
	s_waitcnt lgkmcnt(3)
	v_mfma_f32_32x32x16_bf16 v[144:159], v[80:83], v[172:175], v[144:159]
	v_exp_f32_e32 v140, v112
	v_exp_f32_e32 v141, v113
	v_exp_f32_e32 v142, v114
	v_exp_f32_e32 v143, v115
	s_waitcnt lgkmcnt(1)
	v_mfma_f32_32x32x16_bf16 v[96:111], v[88:91], v[172:175], v[96:111]
	v_exp_f32_e32 v187, v116
	v_exp_f32_e32 v210, v117
	v_exp_f32_e32 v211, v118
	v_exp_f32_e32 v212, v119
	v_mfma_f32_32x32x16_bf16 v[144:159], v[84:87], v[168:171], v[144:159]
	v_exp_f32_e32 v116, v120
	v_exp_f32_e32 v117, v121
	v_exp_f32_e32 v118, v122
	v_exp_f32_e32 v119, v123
	s_waitcnt lgkmcnt(0)
	v_mfma_f32_32x32x16_bf16 v[96:111], v[92:95], v[168:171], v[96:111]
	v_exp_f32_e32 v120, v124
	v_exp_f32_e32 v121, v125
	v_exp_f32_e32 v122, v126
	v_exp_f32_e32 v123, v127
	s_cmp_gt_i32 s26, 2
	s_cselect_b32 s27, -3, 2
	s_add_i32 s27, s27, s26
	s_mulk_i32 s27, 0x2400
	s_waitcnt vmcnt(3)
	ds_write_b128 v208, v[2:5] offset:9216
	v_add_u32_e32 v2, s27, v208
	s_add_i32 s27, s26, 1
	s_cmp_lg_u32 s26, 4
	s_cselect_b32 s26, s27, 0
	s_add_i32 s27, s13, -5
	s_min_u32 s27, s27, s12
	s_lshl_b32 s92, s27, 13
	s_waitcnt vmcnt(2)
	ds_write_b128 v2, v[6:9] offset:36864
	s_add_u32 vcc_lo, s100, s92
	s_addc_u32 vcc_hi, s101, 0
	global_load_dwordx4 v[6:9], v248, vcc
	s_lshl_b32 s92, s28, 7
	s_add_u32 vcc_lo, s98, s92
	s_addc_u32 vcc_hi, s99, 0
	global_load_dwordx4 v[2:5], v249, vcc
	s_nop 0
	s_mul_i32 s28, s26, 0x2400
	s_add_i32 s29, s28, 0xffffdc00
	s_cmp_lg_u32 s26, 0
	s_cselect_b32 s29, s29, 0x9000
	v_add_u32_e32 v92, s29, v195
	ds_read_b128 v[64:67], v92 offset:36864
	ds_read_b128 v[68:71], v92 offset:36896
	ds_read_b128 v[72:75], v92 offset:41472
	ds_read_b128 v[76:79], v92 offset:41504
	ds_read_b128 v[80:83], v92 offset:36928
	ds_read_b128 v[84:87], v92 offset:36960
	ds_read_b128 v[88:91], v92 offset:41536
	ds_read_b128 v[92:95], v92 offset:41568
	s_setprio 3
	v_cvt_pk_bf16_f32 v112, v166, v167
	v_cvt_pk_bf16_f32 v113, v185, v186
	v_cvt_pk_bf16_f32 v114, v128, v129
	v_cvt_pk_bf16_f32 v115, v130, v131
	s_waitcnt lgkmcnt(7)
	s_nop 0
	v_mfma_f32_32x32x16_bf16 v[16:31], v[64:67], v[112:115], v[16:31]
	v_mov_b32_e32 v213, v166
	v_add_f32_e32 v213, v213, v167
	v_add_f32_e32 v213, v213, v185
	v_add_f32_e32 v213, v213, v186
	s_waitcnt lgkmcnt(5)
	v_mfma_f32_32x32x16_bf16 v[32:47], v[72:75], v[112:115], v[32:47]
	v_cvt_pk_bf16_f32 v64, v132, v133
	v_cvt_pk_bf16_f32 v65, v134, v135
	v_cvt_pk_bf16_f32 v66, v136, v137
	v_cvt_pk_bf16_f32 v67, v138, v139
	v_add_f32_e32 v213, v213, v128
	v_add_f32_e32 v213, v213, v129
	v_add_f32_e32 v213, v213, v130
	v_add_f32_e32 v213, v213, v131
	s_nop 0
	v_mfma_f32_32x32x16_bf16 v[16:31], v[68:71], v[64:67], v[16:31]
	v_add_f32_e32 v213, v213, v132
	v_add_f32_e32 v213, v213, v133
	v_add_f32_e32 v213, v213, v134
	v_add_f32_e32 v213, v213, v135
	s_waitcnt lgkmcnt(4)
	v_mfma_f32_32x32x16_bf16 v[32:47], v[76:79], v[64:67], v[32:47]
	v_cvt_pk_bf16_f32 v68, v140, v141
	v_cvt_pk_bf16_f32 v69, v142, v143
	v_cvt_pk_bf16_f32 v70, v187, v210
	v_cvt_pk_bf16_f32 v71, v211, v212
	v_add_f32_e32 v213, v213, v136
	v_add_f32_e32 v213, v213, v137
	v_add_f32_e32 v213, v213, v138
	v_add_f32_e32 v213, v213, v139
	s_waitcnt lgkmcnt(3)
	v_mfma_f32_32x32x16_bf16 v[16:31], v[80:83], v[68:71], v[16:31]
	v_add_f32_e32 v213, v213, v140
	v_add_f32_e32 v213, v213, v141
	v_add_f32_e32 v213, v213, v142
	v_add_f32_e32 v213, v213, v143
	s_waitcnt lgkmcnt(1)
	v_mfma_f32_32x32x16_bf16 v[32:47], v[88:91], v[68:71], v[32:47]
	v_cvt_pk_bf16_f32 v64, v116, v117
	v_cvt_pk_bf16_f32 v65, v118, v119
	v_cvt_pk_bf16_f32 v66, v120, v121
	v_cvt_pk_bf16_f32 v67, v122, v123
	v_add_f32_e32 v213, v213, v187
	v_add_f32_e32 v213, v213, v210
	v_add_f32_e32 v213, v213, v211
	v_add_f32_e32 v213, v213, v212
	s_nop 0
	v_mfma_f32_32x32x16_bf16 v[16:31], v[84:87], v[64:67], v[16:31]
	v_add_f32_e32 v213, v213, v116
	v_add_f32_e32 v213, v213, v117
	v_add_f32_e32 v213, v213, v118
	v_add_f32_e32 v213, v213, v119
	s_waitcnt lgkmcnt(0)
	v_mfma_f32_32x32x16_bf16 v[32:47], v[92:95], v[64:67], v[32:47]
	v_add_f32_e32 v213, v213, v120
	v_add_f32_e32 v213, v213, v121
	v_add_f32_e32 v213, v213, v122
	v_add_f32_e32 v213, v213, v123
	s_setprio 2
	s_waitcnt lgkmcnt(0)
	s_barrier
	ds_read_b128 v[240:243], v195
	ds_read_b128 v[244:247], v195 offset:4608
	ds_read_b128 v[116:119], v195 offset:32
	ds_read_b128 v[120:123], v195 offset:4640
	ds_read_b128 v[124:127], v195 offset:64
	ds_read_b128 v[128:131], v195 offset:4672
	ds_read_b128 v[132:135], v195 offset:96
	ds_read_b128 v[136:139], v195 offset:4704
	v_add_f32_e32 v1, v1, v184
	s_waitcnt lgkmcnt(6)
	v_mfma_f32_32x32x16_bf16 v[80:95], v[240:243], v[180:183], v[48:63]
	v_exp_f32_e32 v140, v144
	v_exp_f32_e32 v141, v145
	v_exp_f32_e32 v142, v146
	v_exp_f32_e32 v143, v147
	v_mfma_f32_32x32x16_bf16 v[64:79], v[244:247], v[180:183], v[48:63]
	v_exp_f32_e32 v144, v148
	v_exp_f32_e32 v145, v149
	v_exp_f32_e32 v146, v150
	v_exp_f32_e32 v147, v151
	s_waitcnt lgkmcnt(5)
	v_mfma_f32_32x32x16_bf16 v[80:95], v[116:119], v[176:179], v[80:95]
	v_exp_f32_e32 v148, v152
	v_exp_f32_e32 v149, v153
	v_exp_f32_e32 v150, v154
	v_exp_f32_e32 v151, v155
	s_waitcnt lgkmcnt(4)
	v_mfma_f32_32x32x16_bf16 v[64:79], v[120:123], v[176:179], v[64:79]
	v_exp_f32_e32 v152, v156
	v_exp_f32_e32 v153, v157
	v_exp_f32_e32 v154, v158
	v_exp_f32_e32 v155, v159
	s_waitcnt lgkmcnt(3)
	v_mfma_f32_32x32x16_bf16 v[80:95], v[124:127], v[172:175], v[80:95]
	v_exp_f32_e32 v156, v96
	v_exp_f32_e32 v157, v97
	v_exp_f32_e32 v158, v98
	v_exp_f32_e32 v159, v99
	s_waitcnt lgkmcnt(2)
	v_mfma_f32_32x32x16_bf16 v[64:79], v[128:131], v[172:175], v[64:79]
	v_exp_f32_e32 v166, v100
	v_exp_f32_e32 v167, v101
	v_exp_f32_e32 v184, v102
	v_exp_f32_e32 v185, v103
	s_waitcnt lgkmcnt(1)
	v_mfma_f32_32x32x16_bf16 v[80:95], v[132:135], v[168:171], v[80:95]
	v_exp_f32_e32 v186, v104
	v_exp_f32_e32 v187, v105
	v_exp_f32_e32 v210, v106
	v_exp_f32_e32 v211, v107
	s_waitcnt lgkmcnt(0)
	v_mfma_f32_32x32x16_bf16 v[64:79], v[136:139], v[168:171], v[64:79]
	v_exp_f32_e32 v212, v108
	v_exp_f32_e32 v214, v109
	v_exp_f32_e32 v215, v110
	v_exp_f32_e32 v216, v111
	s_cmp_gt_i32 s26, 2
	s_cselect_b32 s29, -3, 2
	s_add_i32 s29, s29, s26
	s_mulk_i32 s29, 0x2400
	s_waitcnt vmcnt(3)
	ds_write_b128 v208, v[10:13] offset:18432
	v_add_u32_e32 v10, s29, v208
	s_mov_b32 s29, 0x1da90000
	s_waitcnt vmcnt(2)
	ds_write_b128 v10, v[160:163] offset:36864
	v_add_co_u32_e32 v10, vcc, s29, v164
	s_lshl_b32 s92, s27, 7
	s_nop 0
	v_addc_co_u32_e32 v11, vcc, 0, v165, vcc
	global_load_dwordx4 v[128:131], v[10:11], off
	s_add_u32 vcc_lo, s98, s92
	s_addc_u32 vcc_hi, s99, 0
	global_load_dwordx4 v[10:13], v249, vcc
	v_add_u32_e32 v124, s28, v195
	ds_read_b128 v[240:243], v195 offset:9216
	ds_read_b128 v[244:247], v195 offset:13824
	ds_read_b128 v[96:99], v124 offset:41472
	ds_read_b128 v[100:103], v124 offset:36864
	ds_read_b128 v[104:107], v124 offset:36896
	ds_read_b128 v[108:111], v124 offset:41504
	ds_read_b128 v[112:115], v124 offset:36928
	ds_read_b128 v[116:119], v124 offset:41536
	ds_read_b128 v[120:123], v124 offset:36960
	ds_read_b128 v[124:127], v124 offset:41568
	v_add_f32_e32 v1, v1, v213
	s_add_i32 s28, s26, 1
	s_setprio 1
	v_cvt_pk_bf16_f32 v132, v140, v141
	v_cvt_pk_bf16_f32 v133, v142, v143
	v_cvt_pk_bf16_f32 v134, v144, v145
	v_cvt_pk_bf16_f32 v135, v146, v147
	s_waitcnt lgkmcnt(6)
	s_nop 0
	v_mfma_f32_32x32x16_bf16 v[16:31], v[100:103], v[132:135], v[16:31]
	v_mov_b32_e32 v160, v140
	v_add_f32_e32 v160, v160, v141
	v_add_f32_e32 v160, v160, v142
	v_add_f32_e32 v160, v160, v143
	s_nop 0
	v_mfma_f32_32x32x16_bf16 v[32:47], v[96:99], v[132:135], v[32:47]
	v_cvt_pk_bf16_f32 v100, v148, v149
	v_cvt_pk_bf16_f32 v101, v150, v151
	v_cvt_pk_bf16_f32 v102, v152, v153
	v_cvt_pk_bf16_f32 v103, v154, v155
	v_add_f32_e32 v160, v160, v144
	v_add_f32_e32 v160, v160, v145
	v_add_f32_e32 v160, v160, v146
	v_add_f32_e32 v160, v160, v147
	s_waitcnt lgkmcnt(5)
	v_mfma_f32_32x32x16_bf16 v[16:31], v[104:107], v[100:103], v[16:31]
	v_add_f32_e32 v160, v160, v148
	v_add_f32_e32 v160, v160, v149
	v_add_f32_e32 v160, v160, v150
	v_add_f32_e32 v160, v160, v151
	s_waitcnt lgkmcnt(4)
	v_mfma_f32_32x32x16_bf16 v[32:47], v[108:111], v[100:103], v[32:47]
	v_cvt_pk_bf16_f32 v96, v156, v157
	v_cvt_pk_bf16_f32 v97, v158, v159
	v_cvt_pk_bf16_f32 v98, v166, v167
	v_cvt_pk_bf16_f32 v99, v184, v185
	v_add_f32_e32 v160, v160, v152
	v_add_f32_e32 v160, v160, v153
	v_add_f32_e32 v160, v160, v154
	v_add_f32_e32 v160, v160, v155
	s_waitcnt lgkmcnt(3)
	v_mfma_f32_32x32x16_bf16 v[16:31], v[112:115], v[96:99], v[16:31]
	v_add_f32_e32 v160, v160, v156
	v_add_f32_e32 v160, v160, v157
	v_add_f32_e32 v160, v160, v158
	v_add_f32_e32 v160, v160, v159
	s_waitcnt lgkmcnt(2)
	v_mfma_f32_32x32x16_bf16 v[32:47], v[116:119], v[96:99], v[32:47]
	v_cvt_pk_bf16_f32 v100, v186, v187
	v_cvt_pk_bf16_f32 v101, v210, v211
	v_cvt_pk_bf16_f32 v102, v212, v214
	v_cvt_pk_bf16_f32 v103, v215, v216
	v_add_f32_e32 v160, v160, v166
	v_add_f32_e32 v160, v160, v167
	v_add_f32_e32 v160, v160, v184
	v_add_f32_e32 v160, v160, v185
	s_waitcnt lgkmcnt(1)
	v_mfma_f32_32x32x16_bf16 v[16:31], v[120:123], v[100:103], v[16:31]
	v_add_f32_e32 v160, v160, v186
	v_add_f32_e32 v160, v160, v187
	v_add_f32_e32 v160, v160, v210
	v_add_f32_e32 v160, v160, v211
	s_waitcnt lgkmcnt(0)
	v_mfma_f32_32x32x16_bf16 v[32:47], v[124:127], v[100:103], v[32:47]
	v_add_f32_e32 v160, v160, v212
	v_add_f32_e32 v160, v160, v214
	v_add_f32_e32 v160, v160, v215
	v_add_f32_e32 v160, v160, v216
	s_setprio 0
	ds_read_b128 v[132:135], v195 offset:9248
	ds_read_b128 v[140:143], v195 offset:13856
	ds_read_b128 v[144:147], v195 offset:9280
	ds_read_b128 v[148:151], v195 offset:9312
	ds_read_b128 v[152:155], v195 offset:13888
	ds_read_b128 v[156:159], v195 offset:13920
	s_cmp_lg_u32 s26, 4
	s_cselect_b32 s26, s28, 0
	s_waitcnt lgkmcnt(6)
	v_mfma_f32_32x32x16_bf16 v[112:127], v[240:243], v[180:183], v[48:63]
	v_exp_f32_e32 v161, v80
	v_exp_f32_e32 v162, v81
	v_exp_f32_e32 v163, v82
	v_exp_f32_e32 v164, v83
	s_waitcnt lgkmcnt(5)
	v_mfma_f32_32x32x16_bf16 v[96:111], v[244:247], v[180:183], v[48:63]
	v_exp_f32_e32 v165, v84
	v_exp_f32_e32 v166, v85
	v_exp_f32_e32 v167, v86
	v_exp_f32_e32 v184, v87
	v_mfma_f32_32x32x16_bf16 v[112:127], v[132:135], v[176:179], v[112:127]
	v_exp_f32_e32 v136, v88
	v_exp_f32_e32 v137, v89
	v_exp_f32_e32 v138, v90
	v_exp_f32_e32 v139, v91
	s_waitcnt lgkmcnt(4)
	v_mfma_f32_32x32x16_bf16 v[96:111], v[140:143], v[176:179], v[96:111]
	v_exp_f32_e32 v185, v92
	v_exp_f32_e32 v186, v93
	v_exp_f32_e32 v187, v94
	v_exp_f32_e32 v210, v95
	s_waitcnt lgkmcnt(3)
	v_mfma_f32_32x32x16_bf16 v[112:127], v[144:147], v[172:175], v[112:127]
	v_exp_f32_e32 v140, v64
	v_exp_f32_e32 v141, v65
	v_exp_f32_e32 v142, v66
	v_exp_f32_e32 v143, v67
	s_waitcnt lgkmcnt(1)
	v_mfma_f32_32x32x16_bf16 v[96:111], v[152:155], v[172:175], v[96:111]
	v_exp_f32_e32 v144, v68
	v_exp_f32_e32 v145, v69
	v_exp_f32_e32 v146, v70
	v_exp_f32_e32 v147, v71
	v_mfma_f32_32x32x16_bf16 v[112:127], v[148:151], v[168:171], v[112:127]
	v_exp_f32_e32 v152, v72
	v_exp_f32_e32 v153, v73
	v_exp_f32_e32 v154, v74
	v_exp_f32_e32 v155, v75
	s_waitcnt lgkmcnt(0)
	v_mfma_f32_32x32x16_bf16 v[96:111], v[156:159], v[168:171], v[96:111]
	v_exp_f32_e32 v148, v76
	v_exp_f32_e32 v149, v77
	v_exp_f32_e32 v150, v78
	v_exp_f32_e32 v151, v79
	s_cmp_gt_i32 s26, 2
	s_cselect_b32 s27, -3, 2
	s_add_i32 s27, s27, s26
	s_mulk_i32 s27, 0x2400
	s_waitcnt vmcnt(3)
	ds_write_b128 v208, v[6:9] offset:27648
	v_add_u32_e32 v6, s27, v208
	s_add_i32 s27, s26, 1
	s_cmp_lg_u32 s26, 4
	s_cselect_b32 s27, s27, 0
	s_add_i32 s26, s13, -3
	s_min_u32 s28, s26, s12
	s_lshl_b32 s92, s28, 13
	s_waitcnt vmcnt(2)
	ds_write_b128 v6, v[2:5] offset:36864
	s_add_u32 vcc_lo, s100, s92
	s_addc_u32 vcc_hi, s101, 0
	global_load_dwordx4 v[6:9], v248, vcc
	s_nop 0
	global_load_dwordx4 v[2:5], v[14:15], off offset:1024
	s_mul_i32 s29, s27, 0x2400
	s_add_i32 s34, s29, 0xffffdc00
	s_cmp_lg_u32 s27, 0
	s_cselect_b32 s34, s34, 0x9000
	v_add_u32_e32 v14, s34, v195
	ds_read_b128 v[64:67], v14 offset:36864
	ds_read_b128 v[68:71], v14 offset:36896
	ds_read_b128 v[72:75], v14 offset:41472
	ds_read_b128 v[76:79], v14 offset:41504
	ds_read_b128 v[80:83], v14 offset:36928
	ds_read_b128 v[84:87], v14 offset:36960
	ds_read_b128 v[88:91], v14 offset:41536
	ds_read_b128 v[92:95], v14 offset:41568
	s_setprio 3
	v_cvt_pk_bf16_f32 v132, v161, v162
	v_cvt_pk_bf16_f32 v133, v163, v164
	v_cvt_pk_bf16_f32 v134, v165, v166
	v_cvt_pk_bf16_f32 v135, v167, v184
	s_waitcnt lgkmcnt(7)
	s_nop 0
	v_mfma_f32_32x32x16_bf16 v[16:31], v[64:67], v[132:135], v[16:31]
	v_mov_b32_e32 v14, v161
	v_add_f32_e32 v14, v14, v162
	v_add_f32_e32 v14, v14, v163
	v_add_f32_e32 v14, v14, v164
	s_waitcnt lgkmcnt(5)
	v_mfma_f32_32x32x16_bf16 v[32:47], v[72:75], v[132:135], v[32:47]
	v_cvt_pk_bf16_f32 v64, v136, v137
	v_cvt_pk_bf16_f32 v65, v138, v139
	v_cvt_pk_bf16_f32 v66, v185, v186
	v_cvt_pk_bf16_f32 v67, v187, v210
	v_add_f32_e32 v14, v14, v165
	v_add_f32_e32 v14, v14, v166
	v_add_f32_e32 v14, v14, v167
	v_add_f32_e32 v14, v14, v184
	s_nop 0
	v_mfma_f32_32x32x16_bf16 v[16:31], v[68:71], v[64:67], v[16:31]
	v_add_f32_e32 v14, v14, v136
	v_add_f32_e32 v14, v14, v137
	v_add_f32_e32 v14, v14, v138
	v_add_f32_e32 v14, v14, v139
	s_waitcnt lgkmcnt(4)
	v_mfma_f32_32x32x16_bf16 v[32:47], v[76:79], v[64:67], v[32:47]
	v_cvt_pk_bf16_f32 v68, v140, v141
	v_cvt_pk_bf16_f32 v69, v142, v143
	v_cvt_pk_bf16_f32 v70, v144, v145
	v_cvt_pk_bf16_f32 v71, v146, v147
	v_add_f32_e32 v14, v14, v185
	v_add_f32_e32 v14, v14, v186
	v_add_f32_e32 v14, v14, v187
	v_add_f32_e32 v14, v14, v210
	s_waitcnt lgkmcnt(3)
	v_mfma_f32_32x32x16_bf16 v[16:31], v[80:83], v[68:71], v[16:31]
	v_add_f32_e32 v14, v14, v140
	v_add_f32_e32 v14, v14, v141
	v_add_f32_e32 v14, v14, v142
	v_add_f32_e32 v14, v14, v143
	s_waitcnt lgkmcnt(1)
	v_mfma_f32_32x32x16_bf16 v[32:47], v[88:91], v[68:71], v[32:47]
	v_cvt_pk_bf16_f32 v64, v152, v153
	v_cvt_pk_bf16_f32 v65, v154, v155
	v_cvt_pk_bf16_f32 v66, v148, v149
	v_cvt_pk_bf16_f32 v67, v150, v151
	v_add_f32_e32 v14, v14, v144
	v_add_f32_e32 v14, v14, v145
	v_add_f32_e32 v14, v14, v146
	v_add_f32_e32 v14, v14, v147
	s_nop 0
	v_mfma_f32_32x32x16_bf16 v[16:31], v[84:87], v[64:67], v[16:31]
	v_add_f32_e32 v14, v14, v152
	v_add_f32_e32 v14, v14, v153
	v_add_f32_e32 v14, v14, v154
	v_add_f32_e32 v14, v14, v155
	s_waitcnt lgkmcnt(0)
	v_mfma_f32_32x32x16_bf16 v[32:47], v[92:95], v[64:67], v[32:47]
	v_add_f32_e32 v14, v14, v148
	v_add_f32_e32 v14, v14, v149
	v_add_f32_e32 v14, v14, v150
	v_add_f32_e32 v14, v14, v151
	s_setprio 2
	s_waitcnt lgkmcnt(0)
	s_barrier
	ds_read_b128 v[240:243], v195 offset:18432
	ds_read_b128 v[244:247], v195 offset:23040
	ds_read_b128 v[136:139], v195 offset:18464
	ds_read_b128 v[140:143], v195 offset:23072
	ds_read_b128 v[144:147], v195 offset:18496
	ds_read_b128 v[148:151], v195 offset:23104
	ds_read_b128 v[152:155], v195 offset:18528
	ds_read_b128 v[156:159], v195 offset:23136
	v_add_f32_e32 v1, v1, v160
	s_waitcnt lgkmcnt(6)
	v_mfma_f32_32x32x16_bf16 v[80:95], v[240:243], v[180:183], v[48:63]
	v_exp_f32_e32 v160, v112
	v_exp_f32_e32 v161, v113
	v_exp_f32_e32 v162, v114
	v_exp_f32_e32 v163, v115
	v_mfma_f32_32x32x16_bf16 v[64:79], v[244:247], v[180:183], v[48:63]
	v_exp_f32_e32 v164, v116
	v_exp_f32_e32 v165, v117
	v_exp_f32_e32 v166, v118
	v_exp_f32_e32 v167, v119
	s_waitcnt lgkmcnt(5)
	v_mfma_f32_32x32x16_bf16 v[80:95], v[136:139], v[176:179], v[80:95]
	v_exp_f32_e32 v184, v120
	v_exp_f32_e32 v185, v121
	v_exp_f32_e32 v186, v122
	v_exp_f32_e32 v187, v123
	s_waitcnt lgkmcnt(4)
	v_mfma_f32_32x32x16_bf16 v[64:79], v[140:143], v[176:179], v[64:79]
	v_exp_f32_e32 v136, v124
	v_exp_f32_e32 v137, v125
	v_exp_f32_e32 v138, v126
	v_exp_f32_e32 v139, v127
	s_waitcnt lgkmcnt(3)
	v_mfma_f32_32x32x16_bf16 v[80:95], v[144:147], v[172:175], v[80:95]
	v_exp_f32_e32 v140, v96
	v_exp_f32_e32 v141, v97
	v_exp_f32_e32 v142, v98
	v_exp_f32_e32 v143, v99
	s_waitcnt lgkmcnt(2)
	v_mfma_f32_32x32x16_bf16 v[64:79], v[148:151], v[172:175], v[64:79]
	v_exp_f32_e32 v144, v100
	v_exp_f32_e32 v145, v101
	v_exp_f32_e32 v146, v102
	v_exp_f32_e32 v147, v103
	s_waitcnt lgkmcnt(1)
	v_mfma_f32_32x32x16_bf16 v[80:95], v[152:155], v[168:171], v[80:95]
	v_exp_f32_e32 v148, v104
	v_exp_f32_e32 v149, v105
	v_exp_f32_e32 v150, v106
	v_exp_f32_e32 v151, v107
	s_waitcnt lgkmcnt(0)
	v_mfma_f32_32x32x16_bf16 v[64:79], v[156:159], v[168:171], v[64:79]
	v_exp_f32_e32 v152, v108
	v_exp_f32_e32 v153, v109
	v_exp_f32_e32 v154, v110
	v_exp_f32_e32 v155, v111
	s_cmp_gt_i32 s27, 2
	s_cselect_b32 s34, -3, 2
	s_waitcnt vmcnt(3)
	ds_write_b128 v208, v[128:131]
	s_add_i32 s34, s34, s27
	v_add_u32_e32 v128, s29, v195
	s_add_i32 s29, s13, -2
	s_mulk_i32 s34, 0x2400
	s_min_u32 s29, s29, s12
	v_add_u32_e32 v15, s34, v208
	s_lshl_b32 s92, s29, 13
	s_waitcnt vmcnt(2)
	ds_write_b128 v15, v[10:13] offset:36864
	s_add_u32 vcc_lo, s100, s92
	s_addc_u32 vcc_hi, s101, 0
	global_load_dwordx4 v[10:13], v248, vcc
	s_lshl_b32 s92, s28, 7
	v_add_f32_e32 v1, v1, v14
	s_add_u32 vcc_lo, s98, s92
	s_addc_u32 vcc_hi, s99, 0
	global_load_dwordx4 v[112:115], v249, vcc
	ds_read_b128 v[240:243], v195 offset:27648
	ds_read_b128 v[244:247], v195 offset:32256
	ds_read_b128 v[96:99], v128 offset:41472
	ds_read_b128 v[100:103], v128 offset:36864
	ds_read_b128 v[104:107], v128 offset:36896
	ds_read_b128 v[108:111], v128 offset:41504
	ds_read_b128 v[116:119], v128 offset:36928
	ds_read_b128 v[120:123], v128 offset:41536
	ds_read_b128 v[124:127], v128 offset:36960
	ds_read_b128 v[128:131], v128 offset:41568
	s_add_i32 s34, s27, 1
	s_setprio 1
	v_cvt_pk_bf16_f32 v132, v160, v161
	v_cvt_pk_bf16_f32 v133, v162, v163
	v_cvt_pk_bf16_f32 v134, v164, v165
	v_cvt_pk_bf16_f32 v135, v166, v167
	s_waitcnt lgkmcnt(6)
	s_nop 0
	v_mfma_f32_32x32x16_bf16 v[16:31], v[100:103], v[132:135], v[16:31]
	v_mov_b32_e32 v14, v160
	v_add_f32_e32 v14, v14, v161
	v_add_f32_e32 v14, v14, v162
	v_add_f32_e32 v14, v14, v163
	s_nop 0
	v_mfma_f32_32x32x16_bf16 v[32:47], v[96:99], v[132:135], v[32:47]
	v_cvt_pk_bf16_f32 v100, v184, v185
	v_cvt_pk_bf16_f32 v101, v186, v187
	v_cvt_pk_bf16_f32 v102, v136, v137
	v_cvt_pk_bf16_f32 v103, v138, v139
	v_add_f32_e32 v14, v14, v164
	v_add_f32_e32 v14, v14, v165
	v_add_f32_e32 v14, v14, v166
	v_add_f32_e32 v14, v14, v167
	s_waitcnt lgkmcnt(5)
	v_mfma_f32_32x32x16_bf16 v[16:31], v[104:107], v[100:103], v[16:31]
	v_add_f32_e32 v14, v14, v184
	v_add_f32_e32 v14, v14, v185
	v_add_f32_e32 v14, v14, v186
	v_add_f32_e32 v14, v14, v187
	s_waitcnt lgkmcnt(4)
	v_mfma_f32_32x32x16_bf16 v[32:47], v[108:111], v[100:103], v[32:47]
	v_cvt_pk_bf16_f32 v96, v140, v141
	v_cvt_pk_bf16_f32 v97, v142, v143
	v_cvt_pk_bf16_f32 v98, v144, v145
	v_cvt_pk_bf16_f32 v99, v146, v147
	v_add_f32_e32 v14, v14, v136
	v_add_f32_e32 v14, v14, v137
	v_add_f32_e32 v14, v14, v138
	v_add_f32_e32 v14, v14, v139
	s_waitcnt lgkmcnt(3)
	v_mfma_f32_32x32x16_bf16 v[16:31], v[116:119], v[96:99], v[16:31]
	v_add_f32_e32 v14, v14, v140
	v_add_f32_e32 v14, v14, v141
	v_add_f32_e32 v14, v14, v142
	v_add_f32_e32 v14, v14, v143
	s_waitcnt lgkmcnt(2)
	v_mfma_f32_32x32x16_bf16 v[32:47], v[120:123], v[96:99], v[32:47]
	v_cvt_pk_bf16_f32 v100, v148, v149
	v_cvt_pk_bf16_f32 v101, v150, v151
	v_cvt_pk_bf16_f32 v102, v152, v153
	v_cvt_pk_bf16_f32 v103, v154, v155
	v_add_f32_e32 v14, v14, v144
	v_add_f32_e32 v14, v14, v145
	v_add_f32_e32 v14, v14, v146
	v_add_f32_e32 v14, v14, v147
	s_waitcnt lgkmcnt(1)
	v_mfma_f32_32x32x16_bf16 v[16:31], v[124:127], v[100:103], v[16:31]
	v_add_f32_e32 v14, v14, v148
	v_add_f32_e32 v14, v14, v149
	v_add_f32_e32 v14, v14, v150
	v_add_f32_e32 v14, v14, v151
	s_waitcnt lgkmcnt(0)
	v_mfma_f32_32x32x16_bf16 v[32:47], v[128:131], v[100:103], v[32:47]
	v_add_f32_e32 v14, v14, v152
	v_add_f32_e32 v14, v14, v153
	v_add_f32_e32 v14, v14, v154
	v_add_f32_e32 v14, v14, v155
	s_setprio 0
	ds_read_b128 v[116:119], v195 offset:27680
	ds_read_b128 v[124:127], v195 offset:32288
	ds_read_b128 v[128:131], v195 offset:27712
	ds_read_b128 v[132:135], v195 offset:27744
	ds_read_b128 v[136:139], v195 offset:32320
	ds_read_b128 v[140:143], v195 offset:32352
	s_cmp_lg_u32 s27, 4
	s_cselect_b32 s27, s34, 0
	s_waitcnt lgkmcnt(6)
	v_mfma_f32_32x32x16_bf16 v[152:167], v[240:243], v[180:183], v[48:63]
	v_exp_f32_e32 v15, v80
	v_exp_f32_e32 v144, v81
	v_exp_f32_e32 v145, v82
	v_exp_f32_e32 v146, v83
	s_waitcnt lgkmcnt(5)
	v_mfma_f32_32x32x16_bf16 v[96:111], v[244:247], v[180:183], v[48:63]
	v_exp_f32_e32 v147, v84
	v_exp_f32_e32 v148, v85
	v_exp_f32_e32 v149, v86
	v_exp_f32_e32 v150, v87
	v_mfma_f32_32x32x16_bf16 v[152:167], v[116:119], v[176:179], v[152:167]
	v_exp_f32_e32 v120, v88
	v_exp_f32_e32 v121, v89
	v_exp_f32_e32 v122, v90
	v_exp_f32_e32 v123, v91
	s_waitcnt lgkmcnt(4)
	v_mfma_f32_32x32x16_bf16 v[96:111], v[124:127], v[176:179], v[96:111]
	v_exp_f32_e32 v151, v92
	v_exp_f32_e32 v184, v93
	v_exp_f32_e32 v185, v94
	v_exp_f32_e32 v186, v95
	s_waitcnt lgkmcnt(3)
	v_mfma_f32_32x32x16_bf16 v[152:167], v[128:131], v[172:175], v[152:167]
	v_exp_f32_e32 v124, v64
	v_exp_f32_e32 v125, v65
	v_exp_f32_e32 v126, v66
	v_exp_f32_e32 v127, v67
	s_waitcnt lgkmcnt(1)
	v_mfma_f32_32x32x16_bf16 v[96:111], v[136:139], v[172:175], v[96:111]
	v_exp_f32_e32 v128, v68
	v_exp_f32_e32 v129, v69
	v_exp_f32_e32 v130, v70
	v_exp_f32_e32 v131, v71
	v_mfma_f32_32x32x16_bf16 v[152:167], v[132:135], v[168:171], v[152:167]
	v_exp_f32_e32 v136, v72
	v_exp_f32_e32 v137, v73
	v_exp_f32_e32 v138, v74
	v_exp_f32_e32 v139, v75
	s_waitcnt lgkmcnt(0)
	v_mfma_f32_32x32x16_bf16 v[96:111], v[140:143], v[168:171], v[96:111]
	v_exp_f32_e32 v132, v76
	v_exp_f32_e32 v133, v77
	v_exp_f32_e32 v134, v78
	v_exp_f32_e32 v135, v79
	s_cmp_gt_i32 s27, 2
	s_cselect_b32 s28, -3, 2
	s_add_i32 s28, s28, s27
	s_mulk_i32 s28, 0x2400
	s_waitcnt vmcnt(3)
	ds_write_b128 v208, v[6:9] offset:9216
	v_add_u32_e32 v6, s28, v208
	s_add_i32 s28, s27, 1
	s_cmp_lg_u32 s27, 4
	s_cselect_b32 s27, s28, 0
	s_add_i32 s28, s13, -1
	s_min_u32 s28, s28, s12
	s_lshl_b32 s92, s28, 13
	s_waitcnt vmcnt(2)
	ds_write_b128 v6, v[2:5] offset:36864
	s_add_u32 vcc_lo, s100, s92
	s_addc_u32 vcc_hi, s101, 0
	global_load_dwordx4 v[6:9], v248, vcc
	s_lshl_b32 s92, s29, 7
	s_add_u32 vcc_lo, s98, s92
	s_addc_u32 vcc_hi, s99, 0
	global_load_dwordx4 v[2:5], v249, vcc
	s_nop 0
	s_mul_i32 s29, s27, 0x2400
	s_add_i32 s34, s29, 0xffffdc00
	s_cmp_lg_u32 s27, 0
	s_cselect_b32 s34, s34, 0x9000
	v_add_u32_e32 v92, s34, v195
	ds_read_b128 v[64:67], v92 offset:36864
	ds_read_b128 v[68:71], v92 offset:36896
	ds_read_b128 v[72:75], v92 offset:41472
	ds_read_b128 v[76:79], v92 offset:41504
	ds_read_b128 v[80:83], v92 offset:36928
	ds_read_b128 v[84:87], v92 offset:36960
	ds_read_b128 v[88:91], v92 offset:41536
	ds_read_b128 v[92:95], v92 offset:41568
	s_setprio 3
	v_cvt_pk_bf16_f32 v116, v15, v144
	v_cvt_pk_bf16_f32 v117, v145, v146
	v_cvt_pk_bf16_f32 v118, v147, v148
	v_cvt_pk_bf16_f32 v119, v149, v150
	s_waitcnt lgkmcnt(7)
	s_nop 0
	v_mfma_f32_32x32x16_bf16 v[16:31], v[64:67], v[116:119], v[16:31]
	v_mov_b32_e32 v187, v15
	v_add_f32_e32 v187, v187, v144
	v_add_f32_e32 v187, v187, v145
	v_add_f32_e32 v187, v187, v146
	s_waitcnt lgkmcnt(5)
	v_mfma_f32_32x32x16_bf16 v[32:47], v[72:75], v[116:119], v[32:47]
	v_cvt_pk_bf16_f32 v64, v120, v121
	v_cvt_pk_bf16_f32 v65, v122, v123
	v_cvt_pk_bf16_f32 v66, v151, v184
	v_cvt_pk_bf16_f32 v67, v185, v186
	v_add_f32_e32 v187, v187, v147
	v_add_f32_e32 v187, v187, v148
	v_add_f32_e32 v187, v187, v149
	v_add_f32_e32 v187, v187, v150
	s_nop 0
	v_mfma_f32_32x32x16_bf16 v[16:31], v[68:71], v[64:67], v[16:31]
	v_add_f32_e32 v187, v187, v120
	v_add_f32_e32 v187, v187, v121
	v_add_f32_e32 v187, v187, v122
	v_add_f32_e32 v187, v187, v123
	s_waitcnt lgkmcnt(4)
	v_mfma_f32_32x32x16_bf16 v[32:47], v[76:79], v[64:67], v[32:47]
	v_cvt_pk_bf16_f32 v68, v124, v125
	v_cvt_pk_bf16_f32 v69, v126, v127
	v_cvt_pk_bf16_f32 v70, v128, v129
	v_cvt_pk_bf16_f32 v71, v130, v131
	v_add_f32_e32 v187, v187, v151
	v_add_f32_e32 v187, v187, v184
	v_add_f32_e32 v187, v187, v185
	v_add_f32_e32 v187, v187, v186
	s_waitcnt lgkmcnt(3)
	v_mfma_f32_32x32x16_bf16 v[16:31], v[80:83], v[68:71], v[16:31]
	v_add_f32_e32 v187, v187, v124
	v_add_f32_e32 v187, v187, v125
	v_add_f32_e32 v187, v187, v126
	v_add_f32_e32 v187, v187, v127
	s_waitcnt lgkmcnt(1)
	v_mfma_f32_32x32x16_bf16 v[32:47], v[88:91], v[68:71], v[32:47]
	v_cvt_pk_bf16_f32 v64, v136, v137
	v_cvt_pk_bf16_f32 v65, v138, v139
	v_cvt_pk_bf16_f32 v66, v132, v133
	v_cvt_pk_bf16_f32 v67, v134, v135
	v_add_f32_e32 v187, v187, v128
	v_add_f32_e32 v187, v187, v129
	v_add_f32_e32 v187, v187, v130
	v_add_f32_e32 v187, v187, v131
	s_nop 0
	v_mfma_f32_32x32x16_bf16 v[16:31], v[84:87], v[64:67], v[16:31]
	v_add_f32_e32 v187, v187, v136
	v_add_f32_e32 v187, v187, v137
	v_add_f32_e32 v187, v187, v138
	v_add_f32_e32 v187, v187, v139
	s_waitcnt lgkmcnt(0)
	v_mfma_f32_32x32x16_bf16 v[32:47], v[92:95], v[64:67], v[32:47]
	v_add_f32_e32 v187, v187, v132
	v_add_f32_e32 v187, v187, v133
	v_add_f32_e32 v187, v187, v134
	v_add_f32_e32 v187, v187, v135
	s_setprio 2
	s_waitcnt lgkmcnt(0)
	s_barrier
	ds_read_b128 v[240:243], v195
	ds_read_b128 v[244:247], v195 offset:4608
	ds_read_b128 v[72:75], v195 offset:32
	ds_read_b128 v[76:79], v195 offset:4640
	ds_read_b128 v[80:83], v195 offset:64
	ds_read_b128 v[84:87], v195 offset:4672
	ds_read_b128 v[88:91], v195 offset:96
	ds_read_b128 v[92:95], v195 offset:4704
	v_add_f32_e32 v1, v1, v14
	s_waitcnt lgkmcnt(6)
	v_mfma_f32_32x32x16_bf16 v[136:151], v[240:243], v[180:183], v[48:63]
	v_exp_f32_e32 v14, v152
	v_exp_f32_e32 v15, v153
	v_exp_f32_e32 v116, v154
	v_exp_f32_e32 v117, v155
	v_mfma_f32_32x32x16_bf16 v[120:135], v[244:247], v[180:183], v[48:63]
	v_exp_f32_e32 v118, v156
	v_exp_f32_e32 v119, v157
	v_exp_f32_e32 v184, v158
	v_exp_f32_e32 v185, v159
	s_waitcnt lgkmcnt(5)
	v_mfma_f32_32x32x16_bf16 v[136:151], v[72:75], v[176:179], v[136:151]
	v_exp_f32_e32 v186, v160
	v_exp_f32_e32 v210, v161
	v_exp_f32_e32 v211, v162
	v_exp_f32_e32 v212, v163
	s_waitcnt lgkmcnt(4)
	v_mfma_f32_32x32x16_bf16 v[120:135], v[76:79], v[176:179], v[120:135]
	v_exp_f32_e32 v160, v164
	v_exp_f32_e32 v161, v165
	v_exp_f32_e32 v162, v166
	v_exp_f32_e32 v163, v167
	s_waitcnt lgkmcnt(3)
	v_mfma_f32_32x32x16_bf16 v[136:151], v[80:83], v[172:175], v[136:151]
	v_exp_f32_e32 v164, v96
	v_exp_f32_e32 v165, v97
	v_exp_f32_e32 v166, v98
	v_exp_f32_e32 v167, v99
	s_waitcnt lgkmcnt(2)
	v_mfma_f32_32x32x16_bf16 v[120:135], v[84:87], v[172:175], v[120:135]
	v_exp_f32_e32 v96, v100
	v_exp_f32_e32 v97, v101
	v_exp_f32_e32 v98, v102
	v_exp_f32_e32 v99, v103
	s_waitcnt lgkmcnt(1)
	v_mfma_f32_32x32x16_bf16 v[136:151], v[88:91], v[168:171], v[136:151]
	v_exp_f32_e32 v100, v104
	v_exp_f32_e32 v101, v105
	v_exp_f32_e32 v102, v106
	v_exp_f32_e32 v103, v107
	s_waitcnt lgkmcnt(0)
	v_mfma_f32_32x32x16_bf16 v[120:135], v[92:95], v[168:171], v[120:135]
	v_exp_f32_e32 v104, v108
	v_exp_f32_e32 v105, v109
	v_exp_f32_e32 v106, v110
	v_exp_f32_e32 v107, v111
	s_cmp_gt_i32 s27, 2
	s_cselect_b32 s34, -3, 2
	s_add_i32 s34, s34, s27
	s_mulk_i32 s34, 0x2400
	v_add_u32_e32 v88, s29, v195
	s_min_u32 s29, s13, s12
	s_waitcnt vmcnt(3)
	ds_write_b128 v208, v[10:13] offset:18432
	v_add_u32_e32 v10, s34, v208
	s_lshl_b32 s92, s29, 13
	s_waitcnt vmcnt(2)
	ds_write_b128 v10, v[112:115] offset:36864
	s_add_u32 vcc_lo, s100, s92
	s_addc_u32 vcc_hi, s101, 0
	global_load_dwordx4 v[152:155], v248, vcc
	s_lshl_b32 s92, s28, 7
	s_add_u32 vcc_lo, s98, s92
	s_addc_u32 vcc_hi, s99, 0
	global_load_dwordx4 v[156:159], v249, vcc
	ds_read_b128 v[240:243], v195 offset:9216
	ds_read_b128 v[244:247], v195 offset:13824
	ds_read_b128 v[10:13], v88 offset:41472
	ds_read_b128 v[64:67], v88 offset:36864
	ds_read_b128 v[68:71], v88 offset:36896
	ds_read_b128 v[72:75], v88 offset:41504
	ds_read_b128 v[76:79], v88 offset:36928
	ds_read_b128 v[80:83], v88 offset:41536
	ds_read_b128 v[84:87], v88 offset:36960
	ds_read_b128 v[88:91], v88 offset:41568
	v_add_f32_e32 v1, v1, v187
	s_setprio 1
	v_mov_b32_e32 v109, v136
	v_cvt_pk_bf16_f32 v92, v14, v15
	v_cvt_pk_bf16_f32 v93, v116, v117
	v_cvt_pk_bf16_f32 v94, v118, v119
	v_cvt_pk_bf16_f32 v95, v184, v185
	s_waitcnt lgkmcnt(6)
	s_nop 0
	v_mfma_f32_32x32x16_bf16 v[16:31], v[64:67], v[92:95], v[16:31]
	v_max3_f32 v109, v109, v137, v138
	v_max3_f32 v109, v109, v139, v140
	v_mov_b32_e32 v108, v14
	v_add_f32_e32 v108, v108, v15
	v_add_f32_e32 v108, v108, v116
	v_add_f32_e32 v108, v108, v117
	s_nop 0
	v_mfma_f32_32x32x16_bf16 v[32:47], v[10:13], v[92:95], v[32:47]
	v_cvt_pk_bf16_f32 v64, v186, v210
	v_cvt_pk_bf16_f32 v65, v211, v212
	v_cvt_pk_bf16_f32 v66, v160, v161
	v_cvt_pk_bf16_f32 v67, v162, v163
	v_max3_f32 v109, v109, v141, v142
	v_max3_f32 v109, v109, v143, v144
	v_add_f32_e32 v108, v108, v118
	v_add_f32_e32 v108, v108, v119
	v_add_f32_e32 v108, v108, v184
	v_add_f32_e32 v108, v108, v185
	s_waitcnt lgkmcnt(5)
	v_mfma_f32_32x32x16_bf16 v[16:31], v[68:71], v[64:67], v[16:31]
	v_max3_f32 v109, v109, v145, v146
	v_max3_f32 v109, v109, v147, v148
	v_add_f32_e32 v108, v108, v186
	v_add_f32_e32 v108, v108, v210
	v_add_f32_e32 v108, v108, v211
	v_add_f32_e32 v108, v108, v212
	s_waitcnt lgkmcnt(4)
	v_mfma_f32_32x32x16_bf16 v[32:47], v[72:75], v[64:67], v[32:47]
	v_cvt_pk_bf16_f32 v10, v164, v165
	v_cvt_pk_bf16_f32 v11, v166, v167
	v_cvt_pk_bf16_f32 v12, v96, v97
	v_cvt_pk_bf16_f32 v13, v98, v99
	v_max3_f32 v109, v109, v149, v150
	v_max3_f32 v109, v109, v151, v120
	v_add_f32_e32 v108, v108, v160
	v_add_f32_e32 v108, v108, v161
	v_add_f32_e32 v108, v108, v162
	v_add_f32_e32 v108, v108, v163
	s_waitcnt lgkmcnt(3)
	v_mfma_f32_32x32x16_bf16 v[16:31], v[76:79], v[10:13], v[16:31]
	v_max3_f32 v109, v109, v121, v122
	v_max3_f32 v109, v109, v123, v124
	v_add_f32_e32 v108, v108, v164
	v_add_f32_e32 v108, v108, v165
	v_add_f32_e32 v108, v108, v166
	v_add_f32_e32 v108, v108, v167
	s_waitcnt lgkmcnt(2)
	v_mfma_f32_32x32x16_bf16 v[32:47], v[80:83], v[10:13], v[32:47]
	v_cvt_pk_bf16_f32 v64, v100, v101
	v_cvt_pk_bf16_f32 v65, v102, v103
	v_cvt_pk_bf16_f32 v66, v104, v105
	v_cvt_pk_bf16_f32 v67, v106, v107
	v_max3_f32 v109, v109, v125, v126
	v_max3_f32 v109, v109, v127, v128
	v_add_f32_e32 v108, v108, v96
	v_add_f32_e32 v108, v108, v97
	v_add_f32_e32 v108, v108, v98
	v_add_f32_e32 v108, v108, v99
	s_waitcnt lgkmcnt(1)
	v_mfma_f32_32x32x16_bf16 v[16:31], v[84:87], v[64:67], v[16:31]
	v_max3_f32 v109, v109, v129, v130
	v_max3_f32 v109, v109, v131, v132
	v_add_f32_e32 v108, v108, v100
	v_add_f32_e32 v108, v108, v101
	v_add_f32_e32 v108, v108, v102
	v_add_f32_e32 v108, v108, v103
	s_waitcnt lgkmcnt(0)
	v_mfma_f32_32x32x16_bf16 v[32:47], v[88:91], v[64:67], v[32:47]
	v_max3_f32 v109, v109, v133, v134
	v_max3_f32 v109, v109, v135, v135
	v_add_f32_e32 v108, v108, v104
	v_add_f32_e32 v108, v108, v105
	v_add_f32_e32 v108, v108, v106
	v_add_f32_e32 v108, v108, v107
	s_setprio 0
	ds_read_b128 v[164:167], v195 offset:9248
	ds_read_b128 v[160:163], v195 offset:13856
	ds_read_b128 v[74:77], v195 offset:9280
	ds_read_b128 v[66:69], v195 offset:9312
	ds_read_b128 v[70:73], v195 offset:13888
	ds_read_b128 v[10:13], v195 offset:13920
	v_add_f32_e32 v64, v1, v108
	v_mov_b32_e32 v1, v109
	s_nop 1
	v_permlane32_swap_b32_e32 v109, v1
	v_max_f32_e32 v1, v1, v1
	v_max_f32_e32 v14, v109, v109
	v_max_f32_e32 v1, v14, v1
	v_cmp_lt_f32_e32 vcc, s52, v1
	s_cbranch_vccz .LBB0_663
	v_max_f32_e32 v1, v1, v1
	v_max_f32_e32 v14, 0, v1
	v_add_f32_e32 v209, v209, v14
	v_xor_b32_e32 v48, 0x80000000, v209
	v_pk_add_f32 v[136:137], v[136:137], v[14:15] op_sel_hi:[1,0] neg_lo:[0,1] neg_hi:[0,1]
	v_pk_add_f32 v[120:121], v[120:121], v[14:15] op_sel_hi:[1,0] neg_lo:[0,1] neg_hi:[0,1]
	v_pk_add_f32 v[138:139], v[138:139], v[14:15] op_sel_hi:[1,0] neg_lo:[0,1] neg_hi:[0,1]
	v_pk_add_f32 v[122:123], v[122:123], v[14:15] op_sel_hi:[1,0] neg_lo:[0,1] neg_hi:[0,1]
	v_pk_add_f32 v[140:141], v[140:141], v[14:15] op_sel_hi:[1,0] neg_lo:[0,1] neg_hi:[0,1]
	v_pk_add_f32 v[124:125], v[124:125], v[14:15] op_sel_hi:[1,0] neg_lo:[0,1] neg_hi:[0,1]
	v_pk_add_f32 v[142:143], v[142:143], v[14:15] op_sel_hi:[1,0] neg_lo:[0,1] neg_hi:[0,1]
	v_pk_add_f32 v[126:127], v[126:127], v[14:15] op_sel_hi:[1,0] neg_lo:[0,1] neg_hi:[0,1]
	v_pk_add_f32 v[144:145], v[144:145], v[14:15] op_sel_hi:[1,0] neg_lo:[0,1] neg_hi:[0,1]
	v_pk_add_f32 v[128:129], v[128:129], v[14:15] op_sel_hi:[1,0] neg_lo:[0,1] neg_hi:[0,1]
	v_pk_add_f32 v[146:147], v[146:147], v[14:15] op_sel_hi:[1,0] neg_lo:[0,1] neg_hi:[0,1]
	v_pk_add_f32 v[130:131], v[130:131], v[14:15] op_sel_hi:[1,0] neg_lo:[0,1] neg_hi:[0,1]
	v_pk_add_f32 v[148:149], v[148:149], v[14:15] op_sel_hi:[1,0] neg_lo:[0,1] neg_hi:[0,1]
	v_pk_add_f32 v[132:133], v[132:133], v[14:15] op_sel_hi:[1,0] neg_lo:[0,1] neg_hi:[0,1]
	v_pk_add_f32 v[150:151], v[150:151], v[14:15] op_sel_hi:[1,0] neg_lo:[0,1] neg_hi:[0,1]
	v_pk_add_f32 v[134:135], v[134:135], v[14:15] op_sel_hi:[1,0] neg_lo:[0,1] neg_hi:[0,1]
	v_exp_f32_e64 v14, -v14
	v_mov_b32_e32 v49, v48
	v_mov_b32_e32 v50, v48
	v_mov_b32_e32 v51, v48
	v_mov_b32_e32 v52, v48
	v_mov_b32_e32 v53, v48
	v_mov_b32_e32 v54, v48
	v_mov_b32_e32 v55, v48
	v_mov_b32_e32 v56, v48
	v_mov_b32_e32 v57, v48
	v_mov_b32_e32 v58, v48
	v_mov_b32_e32 v59, v48
	v_mov_b32_e32 v60, v48
	v_mov_b32_e32 v61, v48
	v_mov_b32_e32 v62, v48
	v_mov_b32_e32 v63, v48
	s_nop 11
	v_pk_mul_f32 v[30:31], v[30:31], v[14:15] op_sel_hi:[1,0]
	v_pk_mul_f32 v[28:29], v[28:29], v[14:15] op_sel_hi:[1,0]
	v_pk_mul_f32 v[26:27], v[26:27], v[14:15] op_sel_hi:[1,0]
	v_pk_mul_f32 v[24:25], v[24:25], v[14:15] op_sel_hi:[1,0]
	v_pk_mul_f32 v[22:23], v[22:23], v[14:15] op_sel_hi:[1,0]
	v_pk_mul_f32 v[20:21], v[20:21], v[14:15] op_sel_hi:[1,0]
	v_pk_mul_f32 v[18:19], v[18:19], v[14:15] op_sel_hi:[1,0]
	v_pk_mul_f32 v[16:17], v[16:17], v[14:15] op_sel_hi:[1,0]
	v_pk_mul_f32 v[46:47], v[46:47], v[14:15] op_sel_hi:[1,0]
	v_pk_mul_f32 v[44:45], v[44:45], v[14:15] op_sel_hi:[1,0]
	v_pk_mul_f32 v[42:43], v[42:43], v[14:15] op_sel_hi:[1,0]
	v_pk_mul_f32 v[40:41], v[40:41], v[14:15] op_sel_hi:[1,0]
	v_pk_mul_f32 v[38:39], v[38:39], v[14:15] op_sel_hi:[1,0]
	v_pk_mul_f32 v[36:37], v[36:37], v[14:15] op_sel_hi:[1,0]
	v_pk_mul_f32 v[34:35], v[34:35], v[14:15] op_sel_hi:[1,0]
	v_pk_mul_f32 v[32:33], v[32:33], v[14:15] op_sel_hi:[1,0]
	v_mul_f32_e32 v64, v64, v14
